# GEMM loop: load segments at high priority + scalar address arithmetic moved into MFMA segments
# speedup vs baseline: 1.0256x; 1.0256x over previous
.LBB0_176:
	s_mov_b32 m0, s55
	s_nop 0
	global_load_lds_dwordx4 v194, s[100:101]
	s_mov_b32 m0, s67
	s_nop 0
	global_load_lds_dwordx4 v196, s[100:101]
	v_add_u32_e32 v130, 0x10000, v243
	v_add_u32_e32 v142, 0x14000, v243
	ds_read_b128 v[146:149], v130
	ds_read_b128 v[150:153], v130 offset:1024
	ds_read_b128 v[154:157], v130 offset:2048
	ds_read_b128 v[158:161], v130 offset:3072
	ds_read_b128 v[130:133], v142
	ds_read_b128 v[134:137], v142 offset:1024
	ds_read_b128 v[138:141], v142 offset:2048
	ds_read_b128 v[142:145], v142 offset:3072
	v_lshl_add_u64 v[246:247], v[234:235], 0, s[80:81]
	s_add_i32 m0, s8, 0xc000
	s_waitcnt lgkmcnt(0)
	ds_read_b128 v[174:177], v244
	ds_read_b128 v[190:193], v244 offset:1024
	ds_read_b128 v[170:173], v244 offset:2048
	ds_read_b128 v[186:189], v244 offset:3072
	ds_read_b128 v[166:169], v244 offset:4096
	ds_read_b128 v[182:185], v244 offset:5120
	ds_read_b128 v[162:165], v244 offset:6144
	ds_read_b128 v[178:181], v244 offset:7168
	global_load_lds_dwordx4 v[246:247], off
	v_lshl_add_u64 v[246:247], v[236:237], 0, s[80:81]
	s_add_i32 m0, s8, 0xe000
	s_nop 0
	global_load_lds_dwordx4 v[246:247], off
	s_waitcnt vmcnt(8)
	s_waitcnt lgkmcnt(0)
	s_barrier
	s_setprio 0
	s_waitcnt lgkmcnt(0)
	v_mfma_f32_16x16x32_bf16 v[118:121], v[146:149], v[174:177], v[118:121]
	v_mfma_f32_16x16x32_bf16 v[126:129], v[154:157], v[174:177], v[126:129]
	v_mfma_f32_16x16x32_bf16 v[102:105], v[146:149], v[170:173], v[102:105]
	v_mfma_f32_16x16x32_bf16 v[110:113], v[154:157], v[170:173], v[110:113]
	v_mfma_f32_16x16x32_bf16 v[86:89], v[146:149], v[166:169], v[86:89]
	v_mfma_f32_16x16x32_bf16 v[94:97], v[154:157], v[166:169], v[94:97]
	v_mfma_f32_16x16x32_bf16 v[70:73], v[146:149], v[162:165], v[70:73]
	v_mfma_f32_16x16x32_bf16 v[78:81], v[154:157], v[162:165], v[78:81]
	v_mfma_f32_16x16x32_bf16 v[118:121], v[150:153], v[190:193], v[118:121]
	v_mfma_f32_16x16x32_bf16 v[126:129], v[158:161], v[190:193], v[126:129]
	v_mfma_f32_16x16x32_bf16 v[102:105], v[150:153], v[186:189], v[102:105]
	v_mfma_f32_16x16x32_bf16 v[110:113], v[158:161], v[186:189], v[110:113]
	v_mfma_f32_16x16x32_bf16 v[86:89], v[150:153], v[182:185], v[86:89]
	v_mfma_f32_16x16x32_bf16 v[94:97], v[158:161], v[182:185], v[94:97]
	v_mfma_f32_16x16x32_bf16 v[70:73], v[150:153], v[178:181], v[70:73]
	v_mfma_f32_16x16x32_bf16 v[78:81], v[158:161], v[178:181], v[78:81]
	s_setprio 1
	s_setprio 0
	s_add_u32 s82, s0, s80
	s_addc_u32 s83, s1, s81
	s_add_u32 s84, s82, 0x460000
	s_addc_u32 s85, s83, 0
	s_cmp_eq_u32 s80, 0x41a0000
	s_cselect_b64 s[86:87], -1, 0
	s_and_b64 s[82:83], s[86:87], exec
	s_cselect_b32 s83, s71, s97
	s_cselect_b32 s82, s73, s79
	s_cselect_b32 s85, s22, s85
	s_cselect_b32 s84, s69, s84
	v_mfma_f32_16x16x32_bf16 v[122:125], v[130:133], v[174:177], v[122:125]
	v_mfma_f32_16x16x32_bf16 v[114:117], v[138:141], v[174:177], v[114:117]
	v_mfma_f32_16x16x32_bf16 v[106:109], v[130:133], v[170:173], v[106:109]
	v_mfma_f32_16x16x32_bf16 v[98:101], v[138:141], v[170:173], v[98:101]
	v_mfma_f32_16x16x32_bf16 v[90:93], v[130:133], v[166:169], v[90:93]
	v_mfma_f32_16x16x32_bf16 v[82:85], v[138:141], v[166:169], v[82:85]
	v_mfma_f32_16x16x32_bf16 v[74:77], v[130:133], v[162:165], v[74:77]
	v_mfma_f32_16x16x32_bf16 v[66:69], v[138:141], v[162:165], v[66:69]
	v_mfma_f32_16x16x32_bf16 v[122:125], v[134:137], v[190:193], v[122:125]
	v_mfma_f32_16x16x32_bf16 v[114:117], v[142:145], v[190:193], v[114:117]
	v_mfma_f32_16x16x32_bf16 v[106:109], v[134:137], v[186:189], v[106:109]
	v_mfma_f32_16x16x32_bf16 v[98:101], v[142:145], v[186:189], v[98:101]
	v_mfma_f32_16x16x32_bf16 v[90:93], v[134:137], v[182:185], v[90:93]
	v_mfma_f32_16x16x32_bf16 v[82:85], v[142:145], v[182:185], v[82:85]
	v_mfma_f32_16x16x32_bf16 v[74:77], v[134:137], v[178:181], v[74:77]
	v_mfma_f32_16x16x32_bf16 v[66:69], v[142:145], v[178:181], v[66:69]
	s_setprio 1
	s_barrier
	v_cndmask_b32_e64 v246, 0, 1, s[50:51]
	v_cmp_ne_u32_e64 s[48:49], 1, v246
	s_andn2_b64 vcc, exec, s[50:51]
	s_cbranch_vccnz .LBB0_178
	ds_read_b128 v[174:177], v244 offset:16384
	ds_read_b128 v[190:193], v244 offset:17408
	ds_read_b128 v[170:173], v244 offset:18432
	ds_read_b128 v[186:189], v244 offset:19456
	ds_read_b128 v[166:169], v244 offset:20480
	ds_read_b128 v[182:185], v244 offset:21504
	ds_read_b128 v[162:165], v244 offset:22528
	ds_read_b128 v[178:181], v244 offset:23552
.LBB0_178:
	s_mov_b32 m0, s9
	s_add_u32 vcc_lo, s82, 0x4000
	global_load_lds_dwordx4 v194, s[82:83]
	s_mov_b32 m0, s10
	s_addc_u32 vcc_hi, s83, 0
	global_load_lds_dwordx4 v196, s[82:83]
	s_mov_b32 m0, s11
	s_nop 0
	global_load_lds_dwordx4 v194, vcc
	v_lshl_add_u64 v[246:247], vcc, 0, v[196:197]
	s_mov_b32 m0, s12
	s_and_b64 vcc, exec, s[48:49]
	global_load_lds_dwordx4 v[246:247], off
	s_mov_b64 s[98:99], s[84:85]
	s_waitcnt vmcnt(6)
	s_waitcnt lgkmcnt(0)
	s_barrier
	s_cbranch_vccnz .LBB0_180
	s_setprio 0
	s_waitcnt lgkmcnt(0)
	v_mfma_f32_16x16x32_bf16 v[54:57], v[146:149], v[174:177], v[54:57]
	v_mfma_f32_16x16x32_bf16 v[62:65], v[154:157], v[174:177], v[62:65]
	v_mfma_f32_16x16x32_bf16 v[38:41], v[146:149], v[170:173], v[38:41]
	v_mfma_f32_16x16x32_bf16 v[46:49], v[154:157], v[170:173], v[46:49]
	v_mfma_f32_16x16x32_bf16 v[22:25], v[146:149], v[166:169], v[22:25]
	v_mfma_f32_16x16x32_bf16 v[30:33], v[154:157], v[166:169], v[30:33]
	v_mfma_f32_16x16x32_bf16 v[10:13], v[146:149], v[162:165], v[10:13]
	v_mfma_f32_16x16x32_bf16 v[14:17], v[154:157], v[162:165], v[14:17]
	v_mfma_f32_16x16x32_bf16 v[54:57], v[150:153], v[190:193], v[54:57]
	v_mfma_f32_16x16x32_bf16 v[62:65], v[158:161], v[190:193], v[62:65]
	v_mfma_f32_16x16x32_bf16 v[38:41], v[150:153], v[186:189], v[38:41]
	v_mfma_f32_16x16x32_bf16 v[46:49], v[158:161], v[186:189], v[46:49]
	v_mfma_f32_16x16x32_bf16 v[22:25], v[150:153], v[182:185], v[22:25]
	v_mfma_f32_16x16x32_bf16 v[30:33], v[158:161], v[182:185], v[30:33]
	v_mfma_f32_16x16x32_bf16 v[10:13], v[150:153], v[178:181], v[10:13]
	v_mfma_f32_16x16x32_bf16 v[14:17], v[158:161], v[178:181], v[14:17]
	s_setprio 1
	s_setprio 0
	v_mfma_f32_16x16x32_bf16 v[58:61], v[130:133], v[174:177], v[58:61]
	v_mfma_f32_16x16x32_bf16 v[50:53], v[138:141], v[174:177], v[50:53]
	v_mfma_f32_16x16x32_bf16 v[42:45], v[130:133], v[170:173], v[42:45]
	v_mfma_f32_16x16x32_bf16 v[34:37], v[138:141], v[170:173], v[34:37]
	v_mfma_f32_16x16x32_bf16 v[26:29], v[130:133], v[166:169], v[26:29]
	v_mfma_f32_16x16x32_bf16 v[18:21], v[138:141], v[166:169], v[18:21]
	v_mfma_f32_16x16x32_bf16 v[6:9], v[130:133], v[162:165], v[6:9]
	v_mfma_f32_16x16x32_bf16 v[2:5], v[138:141], v[162:165], v[2:5]
	v_mfma_f32_16x16x32_bf16 v[58:61], v[134:137], v[190:193], v[58:61]
	v_mfma_f32_16x16x32_bf16 v[50:53], v[142:145], v[190:193], v[50:53]
	v_mfma_f32_16x16x32_bf16 v[42:45], v[134:137], v[186:189], v[42:45]
	v_mfma_f32_16x16x32_bf16 v[34:37], v[142:145], v[186:189], v[34:37]
	v_mfma_f32_16x16x32_bf16 v[26:29], v[134:137], v[182:185], v[26:29]
	v_mfma_f32_16x16x32_bf16 v[18:21], v[142:145], v[182:185], v[18:21]
	v_mfma_f32_16x16x32_bf16 v[6:9], v[134:137], v[178:181], v[6:9]
	v_mfma_f32_16x16x32_bf16 v[2:5], v[142:145], v[178:181], v[2:5]
	s_setprio 1
.LBB0_180:
	s_and_b64 vcc, s[46:47], s[86:87]
	v_cndmask_b32_e64 v131, v233, 0, vcc
	v_cndmask_b32_e32 v130, v232, v198, vcc
	v_lshl_add_u64 v[246:247], s[84:85], 0, v[130:131]
	s_barrier
	s_mov_b32 m0, s8
	s_nop 0
	global_load_lds_dwordx4 v194, s[98:99]
	s_mov_b32 m0, s13
	s_nop 0
	global_load_lds_dwordx4 v196, s[98:99]
	v_add_u32_e32 v130, 0x18000, v243
	v_add_u32_e32 v142, 0x1c000, v243
	ds_read_b128 v[146:149], v130
	ds_read_b128 v[150:153], v130 offset:1024
	ds_read_b128 v[154:157], v130 offset:2048
	ds_read_b128 v[158:161], v130 offset:3072
	ds_read_b128 v[130:133], v142
	ds_read_b128 v[134:137], v142 offset:1024
	ds_read_b128 v[138:141], v142 offset:2048
	ds_read_b128 v[142:145], v142 offset:3072
	s_mov_b32 m0, s14
	v_lshl_add_u64 v[248:249], v[246:247], 0, v[194:195]
	s_waitcnt lgkmcnt(0)
	ds_read_b128 v[174:177], v244 offset:32768
	ds_read_b128 v[190:193], v244 offset:33792
	ds_read_b128 v[170:173], v244 offset:34816
	ds_read_b128 v[186:189], v244 offset:35840
	ds_read_b128 v[166:169], v244 offset:36864
	ds_read_b128 v[182:185], v244 offset:37888
	ds_read_b128 v[162:165], v244 offset:38912
	ds_read_b128 v[178:181], v244 offset:39936
	global_load_lds_dwordx4 v[248:249], off
	v_lshl_add_u64 v[246:247], v[246:247], 0, v[196:197]
	s_mov_b32 m0, s15
	s_nop 0
	global_load_lds_dwordx4 v[246:247], off
	s_waitcnt vmcnt(8)
	s_waitcnt lgkmcnt(0)
	s_barrier
	s_setprio 0
	s_waitcnt lgkmcnt(0)
	v_mfma_f32_16x16x32_bf16 v[118:121], v[146:149], v[174:177], v[118:121]
	v_mfma_f32_16x16x32_bf16 v[126:129], v[154:157], v[174:177], v[126:129]
	v_mfma_f32_16x16x32_bf16 v[102:105], v[146:149], v[170:173], v[102:105]
	v_mfma_f32_16x16x32_bf16 v[110:113], v[154:157], v[170:173], v[110:113]
	v_mfma_f32_16x16x32_bf16 v[86:89], v[146:149], v[166:169], v[86:89]
	v_mfma_f32_16x16x32_bf16 v[94:97], v[154:157], v[166:169], v[94:97]
	v_mfma_f32_16x16x32_bf16 v[70:73], v[146:149], v[162:165], v[70:73]
	v_mfma_f32_16x16x32_bf16 v[78:81], v[154:157], v[162:165], v[78:81]
	v_mfma_f32_16x16x32_bf16 v[118:121], v[150:153], v[190:193], v[118:121]
	v_mfma_f32_16x16x32_bf16 v[126:129], v[158:161], v[190:193], v[126:129]
	v_mfma_f32_16x16x32_bf16 v[102:105], v[150:153], v[186:189], v[102:105]
	v_mfma_f32_16x16x32_bf16 v[110:113], v[158:161], v[186:189], v[110:113]
	v_mfma_f32_16x16x32_bf16 v[86:89], v[150:153], v[182:185], v[86:89]
	v_mfma_f32_16x16x32_bf16 v[94:97], v[158:161], v[182:185], v[94:97]
	v_mfma_f32_16x16x32_bf16 v[70:73], v[150:153], v[178:181], v[70:73]
	v_mfma_f32_16x16x32_bf16 v[78:81], v[158:161], v[178:181], v[78:81]
	s_setprio 1
	s_setprio 0
	s_add_u32 s86, s82, 0x120000
	s_addc_u32 s87, s83, 0
	s_add_u32 s84, s84, 0x230000
	s_addc_u32 s85, s85, 0
	v_mfma_f32_16x16x32_bf16 v[122:125], v[130:133], v[174:177], v[122:125]
	v_mfma_f32_16x16x32_bf16 v[114:117], v[138:141], v[174:177], v[114:117]
	v_mfma_f32_16x16x32_bf16 v[106:109], v[130:133], v[170:173], v[106:109]
	v_mfma_f32_16x16x32_bf16 v[98:101], v[138:141], v[170:173], v[98:101]
	v_mfma_f32_16x16x32_bf16 v[90:93], v[130:133], v[166:169], v[90:93]
	v_mfma_f32_16x16x32_bf16 v[82:85], v[138:141], v[166:169], v[82:85]
	v_mfma_f32_16x16x32_bf16 v[74:77], v[130:133], v[162:165], v[74:77]
	v_mfma_f32_16x16x32_bf16 v[66:69], v[138:141], v[162:165], v[66:69]
	v_mfma_f32_16x16x32_bf16 v[122:125], v[134:137], v[190:193], v[122:125]
	v_mfma_f32_16x16x32_bf16 v[114:117], v[142:145], v[190:193], v[114:117]
	v_mfma_f32_16x16x32_bf16 v[106:109], v[134:137], v[186:189], v[106:109]
	v_mfma_f32_16x16x32_bf16 v[98:101], v[142:145], v[186:189], v[98:101]
	v_mfma_f32_16x16x32_bf16 v[90:93], v[134:137], v[182:185], v[90:93]
	v_mfma_f32_16x16x32_bf16 v[82:85], v[142:145], v[182:185], v[82:85]
	v_mfma_f32_16x16x32_bf16 v[74:77], v[134:137], v[178:181], v[74:77]
	v_mfma_f32_16x16x32_bf16 v[66:69], v[142:145], v[178:181], v[66:69]
	s_setprio 1
	s_barrier
	s_and_b64 vcc, exec, s[48:49]
	s_cbranch_vccnz .LBB0_182
	ds_read_b128 v[174:177], v244 offset:49152
	ds_read_b128 v[190:193], v244 offset:50176
	ds_read_b128 v[170:173], v244 offset:51200
	ds_read_b128 v[186:189], v244 offset:52224
	ds_read_b128 v[166:169], v244 offset:53248
	ds_read_b128 v[182:185], v244 offset:54272
	ds_read_b128 v[162:165], v244 offset:55296
	ds_read_b128 v[178:181], v244 offset:56320
.LBB0_182:
	s_mov_b32 m0, s17
	s_add_u32 s82, s82, 0x124000
	global_load_lds_dwordx4 v194, s[86:87]
	s_mov_b32 m0, s54
	s_addc_u32 s83, s83, 0
	global_load_lds_dwordx4 v196, s[86:87]
	s_mov_b32 m0, s89
	s_and_b64 vcc, exec, s[48:49]
	global_load_lds_dwordx4 v194, s[82:83]
	s_mov_b32 m0, s90
	s_nop 0
	global_load_lds_dwordx4 v196, s[82:83]
	s_mov_b64 s[100:101], s[84:85]
	s_waitcnt vmcnt(6)
	s_waitcnt lgkmcnt(0)
	s_barrier
	s_cbranch_vccnz .LBB0_175
	s_setprio 0
	s_waitcnt lgkmcnt(0)
	v_mfma_f32_16x16x32_bf16 v[54:57], v[146:149], v[174:177], v[54:57]
	v_mfma_f32_16x16x32_bf16 v[62:65], v[154:157], v[174:177], v[62:65]
	v_mfma_f32_16x16x32_bf16 v[38:41], v[146:149], v[170:173], v[38:41]
	v_mfma_f32_16x16x32_bf16 v[46:49], v[154:157], v[170:173], v[46:49]
	v_mfma_f32_16x16x32_bf16 v[22:25], v[146:149], v[166:169], v[22:25]
	v_mfma_f32_16x16x32_bf16 v[30:33], v[154:157], v[166:169], v[30:33]
	v_mfma_f32_16x16x32_bf16 v[10:13], v[146:149], v[162:165], v[10:13]
	v_mfma_f32_16x16x32_bf16 v[14:17], v[154:157], v[162:165], v[14:17]
	v_mfma_f32_16x16x32_bf16 v[54:57], v[150:153], v[190:193], v[54:57]
	v_mfma_f32_16x16x32_bf16 v[62:65], v[158:161], v[190:193], v[62:65]
	v_mfma_f32_16x16x32_bf16 v[38:41], v[150:153], v[186:189], v[38:41]
	v_mfma_f32_16x16x32_bf16 v[46:49], v[158:161], v[186:189], v[46:49]
	v_mfma_f32_16x16x32_bf16 v[22:25], v[150:153], v[182:185], v[22:25]
	v_mfma_f32_16x16x32_bf16 v[30:33], v[158:161], v[182:185], v[30:33]
	v_mfma_f32_16x16x32_bf16 v[10:13], v[150:153], v[178:181], v[10:13]
	v_mfma_f32_16x16x32_bf16 v[14:17], v[158:161], v[178:181], v[14:17]
	s_setprio 1
	s_setprio 0
	v_mfma_f32_16x16x32_bf16 v[58:61], v[130:133], v[174:177], v[58:61]
	v_mfma_f32_16x16x32_bf16 v[50:53], v[138:141], v[174:177], v[50:53]
	v_mfma_f32_16x16x32_bf16 v[42:45], v[130:133], v[170:173], v[42:45]
	v_mfma_f32_16x16x32_bf16 v[34:37], v[138:141], v[170:173], v[34:37]
	v_mfma_f32_16x16x32_bf16 v[26:29], v[130:133], v[166:169], v[26:29]
	v_mfma_f32_16x16x32_bf16 v[18:21], v[138:141], v[166:169], v[18:21]
	v_mfma_f32_16x16x32_bf16 v[6:9], v[130:133], v[162:165], v[6:9]
	v_mfma_f32_16x16x32_bf16 v[2:5], v[138:141], v[162:165], v[2:5]
	v_mfma_f32_16x16x32_bf16 v[58:61], v[134:137], v[190:193], v[58:61]
	v_mfma_f32_16x16x32_bf16 v[50:53], v[142:145], v[190:193], v[50:53]
	v_mfma_f32_16x16x32_bf16 v[42:45], v[134:137], v[186:189], v[42:45]
	v_mfma_f32_16x16x32_bf16 v[34:37], v[142:145], v[186:189], v[34:37]
	v_mfma_f32_16x16x32_bf16 v[26:29], v[134:137], v[182:185], v[26:29]
	v_mfma_f32_16x16x32_bf16 v[18:21], v[142:145], v[182:185], v[18:21]
	v_mfma_f32_16x16x32_bf16 v[6:9], v[134:137], v[178:181], v[6:9]
	v_mfma_f32_16x16x32_bf16 v[2:5], v[142:145], v[178:181], v[2:5]
	s_setprio 1
	s_branch .LBB0_175

.LBB0_559:
	s_mov_b32 m0, s55
	s_nop 0
	global_load_lds_dwordx4 v194, s[100:101]
	s_mov_b32 m0, s67
	s_nop 0
	global_load_lds_dwordx4 v196, s[100:101]
	ds_read_b128 v[146:149], v227
	ds_read_b128 v[150:153], v227 offset:1024
	ds_read_b128 v[154:157], v227 offset:2048
	ds_read_b128 v[158:161], v227 offset:3072
	ds_read_b128 v[130:133], v228
	ds_read_b128 v[134:137], v228 offset:1024
	ds_read_b128 v[138:141], v228 offset:2048
	ds_read_b128 v[142:145], v228 offset:3072
	v_lshl_add_u64 v[234:235], v[216:217], 0, s[58:59]
	s_add_i32 m0, s8, 0xc000
	s_waitcnt lgkmcnt(0)
	ds_read_b128 v[174:177], v229
	ds_read_b128 v[190:193], v229 offset:1024
	ds_read_b128 v[170:173], v229 offset:2048
	ds_read_b128 v[186:189], v229 offset:3072
	ds_read_b128 v[166:169], v229 offset:4096
	ds_read_b128 v[182:185], v229 offset:5120
	ds_read_b128 v[162:165], v229 offset:6144
	ds_read_b128 v[178:181], v229 offset:7168
	global_load_lds_dwordx4 v[234:235], off
	v_lshl_add_u64 v[234:235], v[218:219], 0, s[58:59]
	s_add_i32 m0, s8, 0xe000
	s_nop 0
	global_load_lds_dwordx4 v[234:235], off
	s_waitcnt vmcnt(8)
	s_waitcnt lgkmcnt(0)
	s_barrier
	s_setprio 0
	s_waitcnt lgkmcnt(0)
	v_mfma_f32_16x16x32_bf16 v[126:129], v[146:149], v[174:177], v[126:129]
	v_mfma_f32_16x16x32_bf16 v[122:125], v[154:157], v[174:177], v[122:125]
	v_mfma_f32_16x16x32_bf16 v[110:113], v[146:149], v[170:173], v[110:113]
	v_mfma_f32_16x16x32_bf16 v[106:109], v[154:157], v[170:173], v[106:109]
	v_mfma_f32_16x16x32_bf16 v[94:97], v[146:149], v[166:169], v[94:97]
	v_mfma_f32_16x16x32_bf16 v[90:93], v[154:157], v[166:169], v[90:93]
	v_mfma_f32_16x16x32_bf16 v[78:81], v[146:149], v[162:165], v[78:81]
	v_mfma_f32_16x16x32_bf16 v[74:77], v[154:157], v[162:165], v[74:77]
	v_mfma_f32_16x16x32_bf16 v[126:129], v[150:153], v[190:193], v[126:129]
	v_mfma_f32_16x16x32_bf16 v[122:125], v[158:161], v[190:193], v[122:125]
	v_mfma_f32_16x16x32_bf16 v[110:113], v[150:153], v[186:189], v[110:113]
	v_mfma_f32_16x16x32_bf16 v[106:109], v[158:161], v[186:189], v[106:109]
	v_mfma_f32_16x16x32_bf16 v[94:97], v[150:153], v[182:185], v[94:97]
	v_mfma_f32_16x16x32_bf16 v[90:93], v[158:161], v[182:185], v[90:93]
	v_mfma_f32_16x16x32_bf16 v[78:81], v[150:153], v[178:181], v[78:81]
	v_mfma_f32_16x16x32_bf16 v[74:77], v[158:161], v[178:181], v[74:77]
	s_setprio 1
	s_setprio 0
	s_add_u32 s60, s56, s58
	s_addc_u32 s61, s57, s59
	s_add_u32 s62, s60, 0x440000
	s_addc_u32 s63, s61, 0
	s_cmp_eq_u32 s58, 0x3fc0000
	s_cselect_b64 s[68:69], -1, 0
	s_and_b64 s[60:61], s[68:69], exec
	s_cselect_b32 s61, s37, s72
	s_cselect_b32 s60, s47, s53
	s_cselect_b32 s63, s1, s63
	s_cselect_b32 s62, s24, s62
	v_mfma_f32_16x16x32_bf16 v[118:121], v[130:133], v[174:177], v[118:121]
	v_mfma_f32_16x16x32_bf16 v[114:117], v[138:141], v[174:177], v[114:117]
	v_mfma_f32_16x16x32_bf16 v[102:105], v[130:133], v[170:173], v[102:105]
	v_mfma_f32_16x16x32_bf16 v[98:101], v[138:141], v[170:173], v[98:101]
	v_mfma_f32_16x16x32_bf16 v[86:89], v[130:133], v[166:169], v[86:89]
	v_mfma_f32_16x16x32_bf16 v[82:85], v[138:141], v[166:169], v[82:85]
	v_mfma_f32_16x16x32_bf16 v[70:73], v[130:133], v[162:165], v[70:73]
	v_mfma_f32_16x16x32_bf16 v[66:69], v[138:141], v[162:165], v[66:69]
	v_mfma_f32_16x16x32_bf16 v[118:121], v[134:137], v[190:193], v[118:121]
	v_mfma_f32_16x16x32_bf16 v[114:117], v[142:145], v[190:193], v[114:117]
	v_mfma_f32_16x16x32_bf16 v[102:105], v[134:137], v[186:189], v[102:105]
	v_mfma_f32_16x16x32_bf16 v[98:101], v[142:145], v[186:189], v[98:101]
	v_mfma_f32_16x16x32_bf16 v[86:89], v[134:137], v[182:185], v[86:89]
	v_mfma_f32_16x16x32_bf16 v[82:85], v[142:145], v[182:185], v[82:85]
	v_mfma_f32_16x16x32_bf16 v[70:73], v[134:137], v[178:181], v[70:73]
	v_mfma_f32_16x16x32_bf16 v[66:69], v[142:145], v[178:181], v[66:69]
	s_setprio 1
	s_barrier
	v_cmp_ne_u32_e64 s[42:43], 1, v233
	s_andn2_b64 vcc, exec, s[44:45]
	s_cbranch_vccnz .LBB0_561
	ds_read_b128 v[174:177], v229 offset:16384
	ds_read_b128 v[190:193], v229 offset:17408
	ds_read_b128 v[170:173], v229 offset:18432
	ds_read_b128 v[186:189], v229 offset:19456
	ds_read_b128 v[166:169], v229 offset:20480
	ds_read_b128 v[182:185], v229 offset:21504
	ds_read_b128 v[162:165], v229 offset:22528
	ds_read_b128 v[178:181], v229 offset:23552
.LBB0_561:
	s_mov_b32 m0, s9
	s_add_u32 s74, s60, 0x4000
	global_load_lds_dwordx4 v194, s[60:61]
	s_mov_b32 m0, s10
	s_addc_u32 s75, s61, 0
	global_load_lds_dwordx4 v196, s[60:61]
	s_mov_b32 m0, s11
	s_and_b64 vcc, exec, s[42:43]
	global_load_lds_dwordx4 v194, s[74:75]
	s_mov_b32 m0, s12
	s_nop 0
	global_load_lds_dwordx4 v196, s[74:75]
	s_mov_b64 s[98:99], s[62:63]
	s_waitcnt vmcnt(6)
	s_waitcnt lgkmcnt(0)
	s_barrier
	s_cbranch_vccnz .LBB0_563
	s_setprio 0
	s_waitcnt lgkmcnt(0)
	v_mfma_f32_16x16x32_bf16 v[62:65], v[146:149], v[174:177], v[62:65]
	v_mfma_f32_16x16x32_bf16 v[58:61], v[154:157], v[174:177], v[58:61]
	v_mfma_f32_16x16x32_bf16 v[46:49], v[146:149], v[170:173], v[46:49]
	v_mfma_f32_16x16x32_bf16 v[42:45], v[154:157], v[170:173], v[42:45]
	v_mfma_f32_16x16x32_bf16 v[30:33], v[146:149], v[166:169], v[30:33]
	v_mfma_f32_16x16x32_bf16 v[26:29], v[154:157], v[166:169], v[26:29]
	v_mfma_f32_16x16x32_bf16 v[14:17], v[146:149], v[162:165], v[14:17]
	v_mfma_f32_16x16x32_bf16 v[10:13], v[154:157], v[162:165], v[10:13]
	v_mfma_f32_16x16x32_bf16 v[62:65], v[150:153], v[190:193], v[62:65]
	v_mfma_f32_16x16x32_bf16 v[58:61], v[158:161], v[190:193], v[58:61]
	v_mfma_f32_16x16x32_bf16 v[46:49], v[150:153], v[186:189], v[46:49]
	v_mfma_f32_16x16x32_bf16 v[42:45], v[158:161], v[186:189], v[42:45]
	v_mfma_f32_16x16x32_bf16 v[30:33], v[150:153], v[182:185], v[30:33]
	v_mfma_f32_16x16x32_bf16 v[26:29], v[158:161], v[182:185], v[26:29]
	v_mfma_f32_16x16x32_bf16 v[14:17], v[150:153], v[178:181], v[14:17]
	v_mfma_f32_16x16x32_bf16 v[10:13], v[158:161], v[178:181], v[10:13]
	s_setprio 1
	s_setprio 0
	v_mfma_f32_16x16x32_bf16 v[54:57], v[130:133], v[174:177], v[54:57]
	v_mfma_f32_16x16x32_bf16 v[50:53], v[138:141], v[174:177], v[50:53]
	v_mfma_f32_16x16x32_bf16 v[38:41], v[130:133], v[170:173], v[38:41]
	v_mfma_f32_16x16x32_bf16 v[34:37], v[138:141], v[170:173], v[34:37]
	v_mfma_f32_16x16x32_bf16 v[22:25], v[130:133], v[166:169], v[22:25]
	v_mfma_f32_16x16x32_bf16 v[18:21], v[138:141], v[166:169], v[18:21]
	v_mfma_f32_16x16x32_bf16 v[6:9], v[130:133], v[162:165], v[6:9]
	v_mfma_f32_16x16x32_bf16 v[2:5], v[138:141], v[162:165], v[2:5]
	v_mfma_f32_16x16x32_bf16 v[54:57], v[134:137], v[190:193], v[54:57]
	v_mfma_f32_16x16x32_bf16 v[50:53], v[142:145], v[190:193], v[50:53]
	v_mfma_f32_16x16x32_bf16 v[38:41], v[134:137], v[186:189], v[38:41]
	v_mfma_f32_16x16x32_bf16 v[34:37], v[142:145], v[186:189], v[34:37]
	v_mfma_f32_16x16x32_bf16 v[22:25], v[134:137], v[182:185], v[22:25]
	v_mfma_f32_16x16x32_bf16 v[18:21], v[142:145], v[182:185], v[18:21]
	v_mfma_f32_16x16x32_bf16 v[6:9], v[134:137], v[178:181], v[6:9]
	v_mfma_f32_16x16x32_bf16 v[2:5], v[142:145], v[178:181], v[2:5]
	s_setprio 1
.LBB0_563:
	s_and_b64 vcc, s[40:41], s[68:69]
	v_cndmask_b32_e64 v131, v215, 0, vcc
	v_cndmask_b32_e32 v130, v214, v198, vcc
	v_lshl_add_u64 v[234:235], s[62:63], 0, v[130:131]
	s_barrier
	s_mov_b32 m0, s8
	s_nop 0
	global_load_lds_dwordx4 v194, s[98:99]
	s_mov_b32 m0, s13
	s_nop 0
	global_load_lds_dwordx4 v196, s[98:99]
	v_add_u32_e32 v130, 0x18000, v226
	v_add_u32_e32 v142, 0x1c000, v226
	ds_read_b128 v[146:149], v130
	ds_read_b128 v[150:153], v130 offset:1024
	ds_read_b128 v[154:157], v130 offset:2048
	ds_read_b128 v[158:161], v130 offset:3072
	ds_read_b128 v[130:133], v142
	ds_read_b128 v[134:137], v142 offset:1024
	ds_read_b128 v[138:141], v142 offset:2048
	ds_read_b128 v[142:145], v142 offset:3072
	s_mov_b32 m0, s14
	v_lshl_add_u64 v[236:237], v[234:235], 0, v[194:195]
	s_waitcnt lgkmcnt(0)
	ds_read_b128 v[174:177], v229 offset:32768
	ds_read_b128 v[190:193], v229 offset:33792
	ds_read_b128 v[170:173], v229 offset:34816
	ds_read_b128 v[186:189], v229 offset:35840
	ds_read_b128 v[166:169], v229 offset:36864
	ds_read_b128 v[182:185], v229 offset:37888
	ds_read_b128 v[162:165], v229 offset:38912
	ds_read_b128 v[178:181], v229 offset:39936
	global_load_lds_dwordx4 v[236:237], off
	v_lshl_add_u64 v[234:235], v[234:235], 0, v[196:197]
	s_mov_b32 m0, s15
	s_nop 0
	global_load_lds_dwordx4 v[234:235], off
	s_waitcnt vmcnt(8)
	s_waitcnt lgkmcnt(0)
	s_barrier
	s_setprio 0
	s_waitcnt lgkmcnt(0)
	v_mfma_f32_16x16x32_bf16 v[126:129], v[146:149], v[174:177], v[126:129]
	v_mfma_f32_16x16x32_bf16 v[122:125], v[154:157], v[174:177], v[122:125]
	v_mfma_f32_16x16x32_bf16 v[110:113], v[146:149], v[170:173], v[110:113]
	v_mfma_f32_16x16x32_bf16 v[106:109], v[154:157], v[170:173], v[106:109]
	v_mfma_f32_16x16x32_bf16 v[94:97], v[146:149], v[166:169], v[94:97]
	v_mfma_f32_16x16x32_bf16 v[90:93], v[154:157], v[166:169], v[90:93]
	v_mfma_f32_16x16x32_bf16 v[78:81], v[146:149], v[162:165], v[78:81]
	v_mfma_f32_16x16x32_bf16 v[74:77], v[154:157], v[162:165], v[74:77]
	v_mfma_f32_16x16x32_bf16 v[126:129], v[150:153], v[190:193], v[126:129]
	v_mfma_f32_16x16x32_bf16 v[122:125], v[158:161], v[190:193], v[122:125]
	v_mfma_f32_16x16x32_bf16 v[110:113], v[150:153], v[186:189], v[110:113]
	v_mfma_f32_16x16x32_bf16 v[106:109], v[158:161], v[186:189], v[106:109]
	v_mfma_f32_16x16x32_bf16 v[94:97], v[150:153], v[182:185], v[94:97]
	v_mfma_f32_16x16x32_bf16 v[90:93], v[158:161], v[182:185], v[90:93]
	v_mfma_f32_16x16x32_bf16 v[78:81], v[150:153], v[178:181], v[78:81]
	v_mfma_f32_16x16x32_bf16 v[74:77], v[158:161], v[178:181], v[74:77]
	s_setprio 1
	s_setprio 0
	s_add_u32 s68, s60, 0x40000
	s_addc_u32 s69, s61, 0
	s_add_u32 s62, s62, 0x220000
	s_addc_u32 s63, s63, 0
	v_mfma_f32_16x16x32_bf16 v[118:121], v[130:133], v[174:177], v[118:121]
	v_mfma_f32_16x16x32_bf16 v[114:117], v[138:141], v[174:177], v[114:117]
	v_mfma_f32_16x16x32_bf16 v[102:105], v[130:133], v[170:173], v[102:105]
	v_mfma_f32_16x16x32_bf16 v[98:101], v[138:141], v[170:173], v[98:101]
	v_mfma_f32_16x16x32_bf16 v[86:89], v[130:133], v[166:169], v[86:89]
	v_mfma_f32_16x16x32_bf16 v[82:85], v[138:141], v[166:169], v[82:85]
	v_mfma_f32_16x16x32_bf16 v[70:73], v[130:133], v[162:165], v[70:73]
	v_mfma_f32_16x16x32_bf16 v[66:69], v[138:141], v[162:165], v[66:69]
	v_mfma_f32_16x16x32_bf16 v[118:121], v[134:137], v[190:193], v[118:121]
	v_mfma_f32_16x16x32_bf16 v[114:117], v[142:145], v[190:193], v[114:117]
	v_mfma_f32_16x16x32_bf16 v[102:105], v[134:137], v[186:189], v[102:105]
	v_mfma_f32_16x16x32_bf16 v[98:101], v[142:145], v[186:189], v[98:101]
	v_mfma_f32_16x16x32_bf16 v[86:89], v[134:137], v[182:185], v[86:89]
	v_mfma_f32_16x16x32_bf16 v[82:85], v[142:145], v[182:185], v[82:85]
	v_mfma_f32_16x16x32_bf16 v[70:73], v[134:137], v[178:181], v[70:73]
	v_mfma_f32_16x16x32_bf16 v[66:69], v[142:145], v[178:181], v[66:69]
	s_setprio 1
	s_barrier
	s_and_b64 vcc, exec, s[42:43]
	s_cbranch_vccnz .LBB0_565
	ds_read_b128 v[174:177], v229 offset:49152
	ds_read_b128 v[190:193], v229 offset:50176
	ds_read_b128 v[170:173], v229 offset:51200
	ds_read_b128 v[186:189], v229 offset:52224
	ds_read_b128 v[166:169], v229 offset:53248
	ds_read_b128 v[182:185], v229 offset:54272
	ds_read_b128 v[162:165], v229 offset:55296
	ds_read_b128 v[178:181], v229 offset:56320
.LBB0_565:
	s_mov_b32 m0, s17
	s_add_u32 s60, s60, 0x44000
	global_load_lds_dwordx4 v194, s[68:69]
	s_mov_b32 m0, s54
	s_addc_u32 s61, s61, 0
	global_load_lds_dwordx4 v196, s[68:69]
	s_mov_b32 m0, s70
	s_and_b64 vcc, exec, s[42:43]
	global_load_lds_dwordx4 v194, s[60:61]
	s_mov_b32 m0, s71
	s_nop 0
	global_load_lds_dwordx4 v196, s[60:61]
	s_mov_b64 s[100:101], s[62:63]
	s_waitcnt vmcnt(6)
	s_waitcnt lgkmcnt(0)
	s_barrier
	s_cbranch_vccnz .LBB0_558
	s_setprio 0
	s_waitcnt lgkmcnt(0)
	v_mfma_f32_16x16x32_bf16 v[62:65], v[146:149], v[174:177], v[62:65]
	v_mfma_f32_16x16x32_bf16 v[58:61], v[154:157], v[174:177], v[58:61]
	v_mfma_f32_16x16x32_bf16 v[46:49], v[146:149], v[170:173], v[46:49]
	v_mfma_f32_16x16x32_bf16 v[42:45], v[154:157], v[170:173], v[42:45]
	v_mfma_f32_16x16x32_bf16 v[30:33], v[146:149], v[166:169], v[30:33]
	v_mfma_f32_16x16x32_bf16 v[26:29], v[154:157], v[166:169], v[26:29]
	v_mfma_f32_16x16x32_bf16 v[14:17], v[146:149], v[162:165], v[14:17]
	v_mfma_f32_16x16x32_bf16 v[10:13], v[154:157], v[162:165], v[10:13]
	v_mfma_f32_16x16x32_bf16 v[62:65], v[150:153], v[190:193], v[62:65]
	v_mfma_f32_16x16x32_bf16 v[58:61], v[158:161], v[190:193], v[58:61]
	v_mfma_f32_16x16x32_bf16 v[46:49], v[150:153], v[186:189], v[46:49]
	v_mfma_f32_16x16x32_bf16 v[42:45], v[158:161], v[186:189], v[42:45]
	v_mfma_f32_16x16x32_bf16 v[30:33], v[150:153], v[182:185], v[30:33]
	v_mfma_f32_16x16x32_bf16 v[26:29], v[158:161], v[182:185], v[26:29]
	v_mfma_f32_16x16x32_bf16 v[14:17], v[150:153], v[178:181], v[14:17]
	v_mfma_f32_16x16x32_bf16 v[10:13], v[158:161], v[178:181], v[10:13]
	s_setprio 1
	s_setprio 0
	v_mfma_f32_16x16x32_bf16 v[54:57], v[130:133], v[174:177], v[54:57]
	v_mfma_f32_16x16x32_bf16 v[50:53], v[138:141], v[174:177], v[50:53]
	v_mfma_f32_16x16x32_bf16 v[38:41], v[130:133], v[170:173], v[38:41]
	v_mfma_f32_16x16x32_bf16 v[34:37], v[138:141], v[170:173], v[34:37]
	v_mfma_f32_16x16x32_bf16 v[22:25], v[130:133], v[166:169], v[22:25]
	v_mfma_f32_16x16x32_bf16 v[18:21], v[138:141], v[166:169], v[18:21]
	v_mfma_f32_16x16x32_bf16 v[6:9], v[130:133], v[162:165], v[6:9]
	v_mfma_f32_16x16x32_bf16 v[2:5], v[138:141], v[162:165], v[2:5]
	v_mfma_f32_16x16x32_bf16 v[54:57], v[134:137], v[190:193], v[54:57]
	v_mfma_f32_16x16x32_bf16 v[50:53], v[142:145], v[190:193], v[50:53]
	v_mfma_f32_16x16x32_bf16 v[38:41], v[134:137], v[186:189], v[38:41]
	v_mfma_f32_16x16x32_bf16 v[34:37], v[142:145], v[186:189], v[34:37]
	v_mfma_f32_16x16x32_bf16 v[22:25], v[134:137], v[182:185], v[22:25]
	v_mfma_f32_16x16x32_bf16 v[18:21], v[142:145], v[182:185], v[18:21]
	v_mfma_f32_16x16x32_bf16 v[6:9], v[134:137], v[178:181], v[6:9]
	v_mfma_f32_16x16x32_bf16 v[2:5], v[142:145], v[178:181], v[2:5]
	s_setprio 1
	s_branch .LBB0_558

.LBB0_761:
	s_mov_b32 m0, s14
	s_nop 0
	global_load_lds_dwordx4 v194, s[100:101]
	s_mov_b32 m0, s15
	s_nop 0
	global_load_lds_dwordx4 v196, s[100:101]
	ds_read_b128 v[130:133], v237
	ds_read_b128 v[134:137], v237 offset:1024
	ds_read_b128 v[138:141], v237 offset:2048
	ds_read_b128 v[142:145], v237 offset:3072
	ds_read_b128 v[146:149], v238
	ds_read_b128 v[150:153], v238 offset:1024
	ds_read_b128 v[154:157], v238 offset:2048
	ds_read_b128 v[158:161], v238 offset:3072
	v_lshl_add_u64 v[208:209], s[0:1], 0, v[202:203]
	s_add_i32 m0, s9, 0xc000
	ds_read_b128 v[162:165], v239
	ds_read_b128 v[166:169], v239 offset:1024
	ds_read_b128 v[170:173], v239 offset:2048
	ds_read_b128 v[174:177], v239 offset:3072
	ds_read_b128 v[178:181], v239 offset:4096
	ds_read_b128 v[182:185], v239 offset:5120
	ds_read_b128 v[186:189], v239 offset:6144
	ds_read_b128 v[190:193], v239 offset:7168
	global_load_lds_dwordx4 v[208:209], off
	v_lshl_add_u64 v[208:209], s[0:1], 0, v[200:201]
	s_add_i32 m0, s9, 0xe000
	s_nop 0
	global_load_lds_dwordx4 v[208:209], off
	s_waitcnt vmcnt(8)
	s_waitcnt lgkmcnt(0)
	s_barrier
	s_setprio 0
	s_waitcnt lgkmcnt(0)
	v_mfma_f32_16x16x32_bf16 v[126:129], v[130:133], v[162:165], v[126:129]
	v_mfma_f32_16x16x32_bf16 v[122:125], v[138:141], v[162:165], v[122:125]
	s_add_u32 s48, s0, 0x21c000
	s_addc_u32 s49, s1, 0
	s_cmp_eq_u32 s67, 28
	s_cselect_b32 s42, s55, s62
	s_cselect_b32 s43, s29, s63
	s_cselect_b32 s52, s45, s48
	s_cselect_b32 s53, s31, s49
	s_add_u32 s50, s42, 0xe0000
	s_addc_u32 s51, s43, 0
	s_add_u32 s48, s52, 0x220000
	s_addc_u32 s49, s53, 0
	v_mfma_f32_16x16x32_bf16 v[118:121], v[130:133], v[170:173], v[118:121]
	v_mfma_f32_16x16x32_bf16 v[114:117], v[138:141], v[170:173], v[114:117]
	v_mfma_f32_16x16x32_bf16 v[110:113], v[130:133], v[178:181], v[110:113]
	v_mfma_f32_16x16x32_bf16 v[106:109], v[138:141], v[178:181], v[106:109]
	v_mfma_f32_16x16x32_bf16 v[102:105], v[130:133], v[186:189], v[102:105]
	v_mfma_f32_16x16x32_bf16 v[98:101], v[138:141], v[186:189], v[98:101]
	v_mfma_f32_16x16x32_bf16 v[126:129], v[134:137], v[166:169], v[126:129]
	v_mfma_f32_16x16x32_bf16 v[122:125], v[142:145], v[166:169], v[122:125]
	v_mfma_f32_16x16x32_bf16 v[118:121], v[134:137], v[174:177], v[118:121]
	v_mfma_f32_16x16x32_bf16 v[114:117], v[142:145], v[174:177], v[114:117]
	v_mfma_f32_16x16x32_bf16 v[110:113], v[134:137], v[182:185], v[110:113]
	v_mfma_f32_16x16x32_bf16 v[106:109], v[142:145], v[182:185], v[106:109]
	v_mfma_f32_16x16x32_bf16 v[102:105], v[134:137], v[190:193], v[102:105]
	v_mfma_f32_16x16x32_bf16 v[98:101], v[142:145], v[190:193], v[98:101]
	s_setprio 1
	s_setprio 0
	v_mfma_f32_16x16x32_bf16 v[62:65], v[146:149], v[162:165], v[62:65]
	s_add_u32 s60, s52, 0x4000
	s_addc_u32 s61, s53, 0
	v_mfma_f32_16x16x32_bf16 v[58:61], v[154:157], v[162:165], v[58:61]
	v_mfma_f32_16x16x32_bf16 v[54:57], v[146:149], v[170:173], v[54:57]
	v_mfma_f32_16x16x32_bf16 v[50:53], v[154:157], v[170:173], v[50:53]
	v_mfma_f32_16x16x32_bf16 v[46:49], v[146:149], v[178:181], v[46:49]
	v_mfma_f32_16x16x32_bf16 v[42:45], v[154:157], v[178:181], v[42:45]
	v_mfma_f32_16x16x32_bf16 v[38:41], v[146:149], v[186:189], v[38:41]
	v_mfma_f32_16x16x32_bf16 v[34:37], v[154:157], v[186:189], v[34:37]
	v_mfma_f32_16x16x32_bf16 v[62:65], v[150:153], v[166:169], v[62:65]
	v_mfma_f32_16x16x32_bf16 v[58:61], v[158:161], v[166:169], v[58:61]
	v_mfma_f32_16x16x32_bf16 v[54:57], v[150:153], v[174:177], v[54:57]
	v_mfma_f32_16x16x32_bf16 v[50:53], v[158:161], v[174:177], v[50:53]
	v_mfma_f32_16x16x32_bf16 v[46:49], v[150:153], v[182:185], v[46:49]
	v_mfma_f32_16x16x32_bf16 v[42:45], v[158:161], v[182:185], v[42:45]
	v_mfma_f32_16x16x32_bf16 v[38:41], v[150:153], v[190:193], v[38:41]
	v_mfma_f32_16x16x32_bf16 v[34:37], v[158:161], v[190:193], v[34:37]
	s_setprio 1
	s_barrier
	s_add_i32 s68, s16, s8
	s_mov_b32 m0, s68
	ds_read_b128 v[162:165], v239 offset:16384
	ds_read_b128 v[166:169], v239 offset:17408
	ds_read_b128 v[170:173], v239 offset:18432
	ds_read_b128 v[174:177], v239 offset:19456
	ds_read_b128 v[178:181], v239 offset:20480
	ds_read_b128 v[182:185], v239 offset:21504
	ds_read_b128 v[186:189], v239 offset:22528
	ds_read_b128 v[190:193], v239 offset:23552
	global_load_lds_dwordx4 v194, s[42:43]
	s_add_i32 m0, s68, 0x2000
	s_add_u32 s68, s42, 0x4000
	s_addc_u32 s69, s43, 0
	s_add_i32 s70, s17, s8
	global_load_lds_dwordx4 v196, s[42:43]
	s_mov_b32 m0, s70
	s_nop 0
	global_load_lds_dwordx4 v194, s[68:69]
	s_add_i32 m0, s70, 0x2000
	s_nop 0
	global_load_lds_dwordx4 v196, s[68:69]
	s_mov_b64 s[98:99], s[52:53]
	s_waitcnt vmcnt(6)
	s_waitcnt lgkmcnt(0)
	s_barrier
	s_setprio 0
	s_waitcnt lgkmcnt(0)
	v_mfma_f32_16x16x32_bf16 v[94:97], v[130:133], v[162:165], v[94:97]
	v_mfma_f32_16x16x32_bf16 v[90:93], v[138:141], v[162:165], v[90:93]
	v_mfma_f32_16x16x32_bf16 v[86:89], v[130:133], v[170:173], v[86:89]
	v_mfma_f32_16x16x32_bf16 v[82:85], v[138:141], v[170:173], v[82:85]
	v_mfma_f32_16x16x32_bf16 v[78:81], v[130:133], v[178:181], v[78:81]
	v_mfma_f32_16x16x32_bf16 v[74:77], v[138:141], v[178:181], v[74:77]
	v_mfma_f32_16x16x32_bf16 v[70:73], v[130:133], v[186:189], v[70:73]
	v_mfma_f32_16x16x32_bf16 v[66:69], v[138:141], v[186:189], v[66:69]
	v_mfma_f32_16x16x32_bf16 v[94:97], v[134:137], v[166:169], v[94:97]
	v_mfma_f32_16x16x32_bf16 v[90:93], v[142:145], v[166:169], v[90:93]
	v_mfma_f32_16x16x32_bf16 v[86:89], v[134:137], v[174:177], v[86:89]
	v_mfma_f32_16x16x32_bf16 v[82:85], v[142:145], v[174:177], v[82:85]
	v_mfma_f32_16x16x32_bf16 v[78:81], v[134:137], v[182:185], v[78:81]
	v_mfma_f32_16x16x32_bf16 v[74:77], v[142:145], v[182:185], v[74:77]
	v_mfma_f32_16x16x32_bf16 v[70:73], v[134:137], v[190:193], v[70:73]
	v_mfma_f32_16x16x32_bf16 v[66:69], v[142:145], v[190:193], v[66:69]
	s_setprio 1
	s_setprio 0
	v_mfma_f32_16x16x32_bf16 v[30:33], v[146:149], v[162:165], v[30:33]
	v_mfma_f32_16x16x32_bf16 v[26:29], v[154:157], v[162:165], v[26:29]
	v_mfma_f32_16x16x32_bf16 v[22:25], v[146:149], v[170:173], v[22:25]
	v_mfma_f32_16x16x32_bf16 v[18:21], v[154:157], v[170:173], v[18:21]
	v_mfma_f32_16x16x32_bf16 v[14:17], v[146:149], v[178:181], v[14:17]
	v_mfma_f32_16x16x32_bf16 v[10:13], v[154:157], v[178:181], v[10:13]
	v_mfma_f32_16x16x32_bf16 v[6:9], v[146:149], v[186:189], v[6:9]
	v_mfma_f32_16x16x32_bf16 v[2:5], v[154:157], v[186:189], v[2:5]
	v_mfma_f32_16x16x32_bf16 v[30:33], v[150:153], v[166:169], v[30:33]
	v_mfma_f32_16x16x32_bf16 v[26:29], v[158:161], v[166:169], v[26:29]
	v_mfma_f32_16x16x32_bf16 v[22:25], v[150:153], v[174:177], v[22:25]
	v_mfma_f32_16x16x32_bf16 v[18:21], v[158:161], v[174:177], v[18:21]
	v_mfma_f32_16x16x32_bf16 v[14:17], v[150:153], v[182:185], v[14:17]
	v_mfma_f32_16x16x32_bf16 v[10:13], v[158:161], v[182:185], v[10:13]
	v_mfma_f32_16x16x32_bf16 v[6:9], v[150:153], v[190:193], v[6:9]
	v_mfma_f32_16x16x32_bf16 v[2:5], v[158:161], v[190:193], v[2:5]
	s_setprio 1
	s_barrier
	s_mov_b32 m0, s9
	s_nop 0
	global_load_lds_dwordx4 v194, s[98:99]
	s_mov_b32 m0, s10
	s_nop 0
	global_load_lds_dwordx4 v196, s[98:99]
	s_add_i32 s52, 0, 0x18000
	s_add_i32 s53, 0, 0x1c000
	v_add_u32_e32 v142, s52, v228
	v_add_u32_e32 v158, s53, v228
	ds_read_b128 v[130:133], v142
	ds_read_b128 v[134:137], v142 offset:1024
	ds_read_b128 v[138:141], v142 offset:2048
	ds_read_b128 v[142:145], v142 offset:3072
	ds_read_b128 v[146:149], v158
	ds_read_b128 v[150:153], v158 offset:1024
	ds_read_b128 v[154:157], v158 offset:2048
	ds_read_b128 v[158:161], v158 offset:3072
	s_mov_b32 m0, s11
	ds_read_b128 v[162:165], v239 offset:32768
	ds_read_b128 v[166:169], v239 offset:33792
	ds_read_b128 v[170:173], v239 offset:34816
	ds_read_b128 v[174:177], v239 offset:35840
	ds_read_b128 v[178:181], v239 offset:36864
	ds_read_b128 v[182:185], v239 offset:37888
	ds_read_b128 v[186:189], v239 offset:38912
	ds_read_b128 v[190:193], v239 offset:39936
	global_load_lds_dwordx4 v194, s[60:61]
	s_mov_b32 m0, s12
	s_nop 0
	global_load_lds_dwordx4 v196, s[60:61]
	s_waitcnt vmcnt(8)
	s_waitcnt lgkmcnt(0)
	s_barrier
	s_setprio 0
	s_waitcnt lgkmcnt(0)
	v_mfma_f32_16x16x32_bf16 v[126:129], v[130:133], v[162:165], v[126:129]
	v_mfma_f32_16x16x32_bf16 v[122:125], v[138:141], v[162:165], v[122:125]
	v_mfma_f32_16x16x32_bf16 v[118:121], v[130:133], v[170:173], v[118:121]
	v_mfma_f32_16x16x32_bf16 v[114:117], v[138:141], v[170:173], v[114:117]
	v_mfma_f32_16x16x32_bf16 v[110:113], v[130:133], v[178:181], v[110:113]
	v_mfma_f32_16x16x32_bf16 v[106:109], v[138:141], v[178:181], v[106:109]
	v_mfma_f32_16x16x32_bf16 v[102:105], v[130:133], v[186:189], v[102:105]
	v_mfma_f32_16x16x32_bf16 v[98:101], v[138:141], v[186:189], v[98:101]
	v_mfma_f32_16x16x32_bf16 v[126:129], v[134:137], v[166:169], v[126:129]
	v_mfma_f32_16x16x32_bf16 v[122:125], v[142:145], v[166:169], v[122:125]
	v_mfma_f32_16x16x32_bf16 v[118:121], v[134:137], v[174:177], v[118:121]
	v_mfma_f32_16x16x32_bf16 v[114:117], v[142:145], v[174:177], v[114:117]
	v_mfma_f32_16x16x32_bf16 v[110:113], v[134:137], v[182:185], v[110:113]
	v_mfma_f32_16x16x32_bf16 v[106:109], v[142:145], v[182:185], v[106:109]
	v_mfma_f32_16x16x32_bf16 v[102:105], v[134:137], v[190:193], v[102:105]
	v_mfma_f32_16x16x32_bf16 v[98:101], v[142:145], v[190:193], v[98:101]
	s_setprio 1
	s_setprio 0
	s_add_i32 s52, s52, s8
	v_mfma_f32_16x16x32_bf16 v[62:65], v[146:149], v[162:165], v[62:65]
	v_mfma_f32_16x16x32_bf16 v[58:61], v[154:157], v[162:165], v[58:61]
	v_mfma_f32_16x16x32_bf16 v[54:57], v[146:149], v[170:173], v[54:57]
	v_mfma_f32_16x16x32_bf16 v[50:53], v[154:157], v[170:173], v[50:53]
	v_mfma_f32_16x16x32_bf16 v[46:49], v[146:149], v[178:181], v[46:49]
	v_mfma_f32_16x16x32_bf16 v[42:45], v[154:157], v[178:181], v[42:45]
	v_mfma_f32_16x16x32_bf16 v[38:41], v[146:149], v[186:189], v[38:41]
	v_mfma_f32_16x16x32_bf16 v[34:37], v[154:157], v[186:189], v[34:37]
	v_mfma_f32_16x16x32_bf16 v[62:65], v[150:153], v[166:169], v[62:65]
	v_mfma_f32_16x16x32_bf16 v[58:61], v[158:161], v[166:169], v[58:61]
	v_mfma_f32_16x16x32_bf16 v[54:57], v[150:153], v[174:177], v[54:57]
	v_mfma_f32_16x16x32_bf16 v[50:53], v[158:161], v[174:177], v[50:53]
	v_mfma_f32_16x16x32_bf16 v[46:49], v[150:153], v[182:185], v[46:49]
	v_mfma_f32_16x16x32_bf16 v[42:45], v[158:161], v[182:185], v[42:45]
	v_mfma_f32_16x16x32_bf16 v[38:41], v[150:153], v[190:193], v[38:41]
	v_mfma_f32_16x16x32_bf16 v[34:37], v[158:161], v[190:193], v[34:37]
	s_setprio 1
	s_barrier
	s_mov_b32 m0, s52
	ds_read_b128 v[162:165], v239 offset:49152
	ds_read_b128 v[166:169], v239 offset:50176
	ds_read_b128 v[170:173], v239 offset:51200
	ds_read_b128 v[174:177], v239 offset:52224
	ds_read_b128 v[178:181], v239 offset:53248
	ds_read_b128 v[182:185], v239 offset:54272
	ds_read_b128 v[186:189], v239 offset:55296
	ds_read_b128 v[190:193], v239 offset:56320
	global_load_lds_dwordx4 v194, s[50:51]
	s_add_i32 m0, s52, 0x2000
	s_add_u32 s42, s42, 0xe4000
	v_lshl_add_u64 v[208:209], s[50:51], 0, v[196:197]
	s_addc_u32 s43, s43, 0
	s_add_i32 s50, s53, s8
	global_load_lds_dwordx4 v[208:209], off
	s_mov_b32 m0, s50
	s_nop 0
	global_load_lds_dwordx4 v194, s[42:43]
	s_add_i32 m0, s50, 0x2000
	s_nop 0
	global_load_lds_dwordx4 v196, s[42:43]
	s_mov_b64 s[100:101], s[48:49]
	s_waitcnt vmcnt(6)
	s_waitcnt lgkmcnt(0)
	s_barrier
	s_setprio 0
	s_waitcnt lgkmcnt(0)
	v_mfma_f32_16x16x32_bf16 v[94:97], v[130:133], v[162:165], v[94:97]
	v_mfma_f32_16x16x32_bf16 v[90:93], v[138:141], v[162:165], v[90:93]
	v_mfma_f32_16x16x32_bf16 v[86:89], v[130:133], v[170:173], v[86:89]
	v_mfma_f32_16x16x32_bf16 v[82:85], v[138:141], v[170:173], v[82:85]
	v_mfma_f32_16x16x32_bf16 v[78:81], v[130:133], v[178:181], v[78:81]
	v_mfma_f32_16x16x32_bf16 v[74:77], v[138:141], v[178:181], v[74:77]
	v_mfma_f32_16x16x32_bf16 v[70:73], v[130:133], v[186:189], v[70:73]
	v_mfma_f32_16x16x32_bf16 v[66:69], v[138:141], v[186:189], v[66:69]
	v_mfma_f32_16x16x32_bf16 v[94:97], v[134:137], v[166:169], v[94:97]
	v_mfma_f32_16x16x32_bf16 v[90:93], v[142:145], v[166:169], v[90:93]
	v_mfma_f32_16x16x32_bf16 v[86:89], v[134:137], v[174:177], v[86:89]
	v_mfma_f32_16x16x32_bf16 v[82:85], v[142:145], v[174:177], v[82:85]
	v_mfma_f32_16x16x32_bf16 v[78:81], v[134:137], v[182:185], v[78:81]
	v_mfma_f32_16x16x32_bf16 v[74:77], v[142:145], v[182:185], v[74:77]
	v_mfma_f32_16x16x32_bf16 v[70:73], v[134:137], v[190:193], v[70:73]
	v_mfma_f32_16x16x32_bf16 v[66:69], v[142:145], v[190:193], v[66:69]
	s_setprio 1
	s_setprio 0
	v_mfma_f32_16x16x32_bf16 v[30:33], v[146:149], v[162:165], v[30:33]
	v_mfma_f32_16x16x32_bf16 v[26:29], v[154:157], v[162:165], v[26:29]
	v_mfma_f32_16x16x32_bf16 v[22:25], v[146:149], v[170:173], v[22:25]
	v_mfma_f32_16x16x32_bf16 v[18:21], v[154:157], v[170:173], v[18:21]
	v_mfma_f32_16x16x32_bf16 v[14:17], v[146:149], v[178:181], v[14:17]
	v_mfma_f32_16x16x32_bf16 v[10:13], v[154:157], v[178:181], v[10:13]
	v_mfma_f32_16x16x32_bf16 v[6:9], v[146:149], v[186:189], v[6:9]
	v_mfma_f32_16x16x32_bf16 v[2:5], v[154:157], v[186:189], v[2:5]
	v_mfma_f32_16x16x32_bf16 v[30:33], v[150:153], v[166:169], v[30:33]
	v_mfma_f32_16x16x32_bf16 v[26:29], v[158:161], v[166:169], v[26:29]
	v_mfma_f32_16x16x32_bf16 v[22:25], v[150:153], v[174:177], v[22:25]
	v_mfma_f32_16x16x32_bf16 v[18:21], v[158:161], v[174:177], v[18:21]
	v_mfma_f32_16x16x32_bf16 v[14:17], v[150:153], v[182:185], v[14:17]
	v_mfma_f32_16x16x32_bf16 v[10:13], v[158:161], v[182:185], v[10:13]
	v_mfma_f32_16x16x32_bf16 v[6:9], v[150:153], v[190:193], v[6:9]
	v_mfma_f32_16x16x32_bf16 v[2:5], v[158:161], v[190:193], v[2:5]
	s_setprio 1
	s_barrier
	s_add_i32 s67, s67, 2
	s_add_u32 s62, s62, 0x1c0000
	s_addc_u32 s63, s63, 0
	s_add_u32 s0, s0, 0x440000
	s_addc_u32 s1, s1, 0
	s_cmp_gt_u32 s67, 29
	s_cbranch_scc0 .LBB0_761
	s_and_b64 vcc, exec, s[26:27]
	s_cbranch_vccz .LBB0_764
	s_barrier

.LBB0_903:
	s_mov_b32 m0, s23
	s_nop 0
	global_load_lds_dwordx4 v194, s[100:101]
	s_mov_b32 m0, s31
	s_nop 0
	global_load_lds_dwordx4 v196, s[100:101]
	ds_read_b128 v[146:149], v225
	ds_read_b128 v[150:153], v225 offset:1024
	ds_read_b128 v[154:157], v225 offset:2048
	ds_read_b128 v[158:161], v225 offset:3072
	ds_read_b128 v[130:133], v227
	ds_read_b128 v[134:137], v227 offset:1024
	ds_read_b128 v[138:141], v227 offset:2048
	ds_read_b128 v[142:145], v227 offset:3072
	v_lshl_add_u64 v[234:235], v[210:211], 0, s[62:63]
	s_add_i32 m0, s8, 0xc000
	s_waitcnt lgkmcnt(0)
	ds_read_b128 v[174:177], v228
	ds_read_b128 v[190:193], v228 offset:1024
	ds_read_b128 v[170:173], v228 offset:2048
	ds_read_b128 v[186:189], v228 offset:3072
	ds_read_b128 v[166:169], v228 offset:4096
	ds_read_b128 v[182:185], v228 offset:5120
	ds_read_b128 v[162:165], v228 offset:6144
	ds_read_b128 v[178:181], v228 offset:7168
	global_load_lds_dwordx4 v[234:235], off
	v_lshl_add_u64 v[234:235], v[212:213], 0, s[62:63]
	s_add_i32 m0, s8, 0xe000
	s_nop 0
	global_load_lds_dwordx4 v[234:235], off
	s_waitcnt vmcnt(8)
	s_waitcnt lgkmcnt(0)
	s_barrier
	s_setprio 0
	s_waitcnt lgkmcnt(0)
	v_mfma_f32_16x16x32_bf16 v[126:129], v[146:149], v[174:177], v[126:129]
	v_mfma_f32_16x16x32_bf16 v[122:125], v[154:157], v[174:177], v[122:125]
	v_mfma_f32_16x16x32_bf16 v[118:121], v[146:149], v[170:173], v[118:121]
	v_mfma_f32_16x16x32_bf16 v[114:117], v[154:157], v[170:173], v[114:117]
	v_mfma_f32_16x16x32_bf16 v[110:113], v[146:149], v[166:169], v[110:113]
	v_mfma_f32_16x16x32_bf16 v[106:109], v[154:157], v[166:169], v[106:109]
	v_mfma_f32_16x16x32_bf16 v[102:105], v[146:149], v[162:165], v[102:105]
	v_mfma_f32_16x16x32_bf16 v[98:101], v[154:157], v[162:165], v[98:101]
	v_mfma_f32_16x16x32_bf16 v[126:129], v[150:153], v[190:193], v[126:129]
	v_mfma_f32_16x16x32_bf16 v[122:125], v[158:161], v[190:193], v[122:125]
	v_mfma_f32_16x16x32_bf16 v[118:121], v[150:153], v[186:189], v[118:121]
	v_mfma_f32_16x16x32_bf16 v[114:117], v[158:161], v[186:189], v[114:117]
	v_mfma_f32_16x16x32_bf16 v[110:113], v[150:153], v[182:185], v[110:113]
	v_mfma_f32_16x16x32_bf16 v[106:109], v[158:161], v[182:185], v[106:109]
	v_mfma_f32_16x16x32_bf16 v[102:105], v[150:153], v[178:181], v[102:105]
	v_mfma_f32_16x16x32_bf16 v[98:101], v[158:161], v[178:181], v[98:101]
	s_setprio 1
	s_setprio 0
	s_add_u32 s68, s0, s62
	s_addc_u32 s69, s1, s63
	s_add_u32 s70, s68, 0x440000
	s_addc_u32 s71, s69, 0
	s_cmp_eq_u32 s62, 0x3fc0000
	s_cselect_b64 s[72:73], -1, 0
	s_and_b64 s[68:69], s[72:73], exec
	s_cselect_b32 s69, s37, s77
	s_cselect_b32 s68, s75, s76
	s_cselect_b32 s71, s35, s71
	s_cselect_b32 s70, s74, s70
	v_mfma_f32_16x16x32_bf16 v[94:97], v[130:133], v[174:177], v[94:97]
	v_mfma_f32_16x16x32_bf16 v[90:93], v[138:141], v[174:177], v[90:93]
	v_mfma_f32_16x16x32_bf16 v[86:89], v[130:133], v[170:173], v[86:89]
	v_mfma_f32_16x16x32_bf16 v[82:85], v[138:141], v[170:173], v[82:85]
	v_mfma_f32_16x16x32_bf16 v[78:81], v[130:133], v[166:169], v[78:81]
	v_mfma_f32_16x16x32_bf16 v[74:77], v[138:141], v[166:169], v[74:77]
	v_mfma_f32_16x16x32_bf16 v[70:73], v[130:133], v[162:165], v[70:73]
	v_mfma_f32_16x16x32_bf16 v[66:69], v[138:141], v[162:165], v[66:69]
	v_mfma_f32_16x16x32_bf16 v[94:97], v[134:137], v[190:193], v[94:97]
	v_mfma_f32_16x16x32_bf16 v[90:93], v[142:145], v[190:193], v[90:93]
	v_mfma_f32_16x16x32_bf16 v[86:89], v[134:137], v[186:189], v[86:89]
	v_mfma_f32_16x16x32_bf16 v[82:85], v[142:145], v[186:189], v[82:85]
	v_mfma_f32_16x16x32_bf16 v[78:81], v[134:137], v[182:185], v[78:81]
	v_mfma_f32_16x16x32_bf16 v[74:77], v[142:145], v[182:185], v[74:77]
	v_mfma_f32_16x16x32_bf16 v[70:73], v[134:137], v[178:181], v[70:73]
	v_mfma_f32_16x16x32_bf16 v[66:69], v[142:145], v[178:181], v[66:69]
	s_setprio 1
	s_barrier
	v_cmp_ne_u32_e64 s[42:43], 1, v233
	s_andn2_b64 vcc, exec, s[44:45]
	s_cbranch_vccnz .LBB0_905
	ds_read_b128 v[174:177], v228 offset:16384
	ds_read_b128 v[190:193], v228 offset:17408
	ds_read_b128 v[170:173], v228 offset:18432
	ds_read_b128 v[186:189], v228 offset:19456
	ds_read_b128 v[166:169], v228 offset:20480
	ds_read_b128 v[182:185], v228 offset:21504
	ds_read_b128 v[162:165], v228 offset:22528
	ds_read_b128 v[178:181], v228 offset:23552
.LBB0_905:
	s_mov_b32 m0, s9
	s_add_u32 s80, s68, 0x4000
	global_load_lds_dwordx4 v194, s[68:69]
	s_mov_b32 m0, s10
	s_addc_u32 s81, s69, 0
	global_load_lds_dwordx4 v196, s[68:69]
	s_mov_b32 m0, s11
	s_and_b64 vcc, exec, s[42:43]
	global_load_lds_dwordx4 v194, s[80:81]
	s_mov_b32 m0, s12
	s_nop 0
	global_load_lds_dwordx4 v196, s[80:81]
	s_mov_b64 s[98:99], s[70:71]
	s_waitcnt vmcnt(6)
	s_waitcnt lgkmcnt(0)
	s_barrier
	s_cbranch_vccnz .LBB0_907
	s_setprio 0
	s_waitcnt lgkmcnt(0)
	v_mfma_f32_16x16x32_bf16 v[62:65], v[146:149], v[174:177], v[62:65]
	v_mfma_f32_16x16x32_bf16 v[58:61], v[154:157], v[174:177], v[58:61]
	v_mfma_f32_16x16x32_bf16 v[54:57], v[146:149], v[170:173], v[54:57]
	v_mfma_f32_16x16x32_bf16 v[50:53], v[154:157], v[170:173], v[50:53]
	v_mfma_f32_16x16x32_bf16 v[46:49], v[146:149], v[166:169], v[46:49]
	v_mfma_f32_16x16x32_bf16 v[42:45], v[154:157], v[166:169], v[42:45]
	v_mfma_f32_16x16x32_bf16 v[38:41], v[146:149], v[162:165], v[38:41]
	v_mfma_f32_16x16x32_bf16 v[34:37], v[154:157], v[162:165], v[34:37]
	v_mfma_f32_16x16x32_bf16 v[62:65], v[150:153], v[190:193], v[62:65]
	v_mfma_f32_16x16x32_bf16 v[58:61], v[158:161], v[190:193], v[58:61]
	v_mfma_f32_16x16x32_bf16 v[54:57], v[150:153], v[186:189], v[54:57]
	v_mfma_f32_16x16x32_bf16 v[50:53], v[158:161], v[186:189], v[50:53]
	v_mfma_f32_16x16x32_bf16 v[46:49], v[150:153], v[182:185], v[46:49]
	v_mfma_f32_16x16x32_bf16 v[42:45], v[158:161], v[182:185], v[42:45]
	v_mfma_f32_16x16x32_bf16 v[38:41], v[150:153], v[178:181], v[38:41]
	v_mfma_f32_16x16x32_bf16 v[34:37], v[158:161], v[178:181], v[34:37]
	s_setprio 1
	s_setprio 0
	v_mfma_f32_16x16x32_bf16 v[30:33], v[130:133], v[174:177], v[30:33]
	v_mfma_f32_16x16x32_bf16 v[26:29], v[138:141], v[174:177], v[26:29]
	v_mfma_f32_16x16x32_bf16 v[22:25], v[130:133], v[170:173], v[22:25]
	v_mfma_f32_16x16x32_bf16 v[18:21], v[138:141], v[170:173], v[18:21]
	v_mfma_f32_16x16x32_bf16 v[14:17], v[130:133], v[166:169], v[14:17]
	v_mfma_f32_16x16x32_bf16 v[10:13], v[138:141], v[166:169], v[10:13]
	v_mfma_f32_16x16x32_bf16 v[6:9], v[130:133], v[162:165], v[6:9]
	v_mfma_f32_16x16x32_bf16 v[2:5], v[138:141], v[162:165], v[2:5]
	v_mfma_f32_16x16x32_bf16 v[30:33], v[134:137], v[190:193], v[30:33]
	v_mfma_f32_16x16x32_bf16 v[26:29], v[142:145], v[190:193], v[26:29]
	v_mfma_f32_16x16x32_bf16 v[22:25], v[134:137], v[186:189], v[22:25]
	v_mfma_f32_16x16x32_bf16 v[18:21], v[142:145], v[186:189], v[18:21]
	v_mfma_f32_16x16x32_bf16 v[14:17], v[134:137], v[182:185], v[14:17]
	v_mfma_f32_16x16x32_bf16 v[10:13], v[142:145], v[182:185], v[10:13]
	v_mfma_f32_16x16x32_bf16 v[6:9], v[134:137], v[178:181], v[6:9]
	v_mfma_f32_16x16x32_bf16 v[2:5], v[142:145], v[178:181], v[2:5]
	s_setprio 1
.LBB0_907:
	s_and_b64 vcc, s[40:41], s[72:73]
	v_cndmask_b32_e64 v131, v209, 0, vcc
	v_cndmask_b32_e32 v130, v208, v198, vcc
	v_lshl_add_u64 v[234:235], s[70:71], 0, v[130:131]
	s_barrier
	s_mov_b32 m0, s8
	s_nop 0
	global_load_lds_dwordx4 v194, s[98:99]
	s_mov_b32 m0, s13
	s_nop 0
	global_load_lds_dwordx4 v196, s[98:99]
	v_add_u32_e32 v130, 0x18000, v224
	v_add_u32_e32 v142, 0x1c000, v224
	ds_read_b128 v[146:149], v130
	ds_read_b128 v[150:153], v130 offset:1024
	ds_read_b128 v[154:157], v130 offset:2048
	ds_read_b128 v[158:161], v130 offset:3072
	ds_read_b128 v[130:133], v142
	ds_read_b128 v[134:137], v142 offset:1024
	ds_read_b128 v[138:141], v142 offset:2048
	ds_read_b128 v[142:145], v142 offset:3072
	s_mov_b32 m0, s14
	v_lshl_add_u64 v[236:237], v[234:235], 0, v[194:195]
	s_waitcnt lgkmcnt(0)
	ds_read_b128 v[174:177], v228 offset:32768
	ds_read_b128 v[190:193], v228 offset:33792
	ds_read_b128 v[170:173], v228 offset:34816
	ds_read_b128 v[186:189], v228 offset:35840
	ds_read_b128 v[166:169], v228 offset:36864
	ds_read_b128 v[182:185], v228 offset:37888
	ds_read_b128 v[162:165], v228 offset:38912
	ds_read_b128 v[178:181], v228 offset:39936
	global_load_lds_dwordx4 v[236:237], off
	v_lshl_add_u64 v[234:235], v[234:235], 0, v[196:197]
	s_mov_b32 m0, s15
	s_nop 0
	global_load_lds_dwordx4 v[234:235], off
	s_waitcnt vmcnt(8)
	s_waitcnt lgkmcnt(0)
	s_barrier
	s_setprio 0
	s_waitcnt lgkmcnt(0)
	v_mfma_f32_16x16x32_bf16 v[126:129], v[146:149], v[174:177], v[126:129]
	v_mfma_f32_16x16x32_bf16 v[122:125], v[154:157], v[174:177], v[122:125]
	v_mfma_f32_16x16x32_bf16 v[118:121], v[146:149], v[170:173], v[118:121]
	v_mfma_f32_16x16x32_bf16 v[114:117], v[154:157], v[170:173], v[114:117]
	v_mfma_f32_16x16x32_bf16 v[110:113], v[146:149], v[166:169], v[110:113]
	v_mfma_f32_16x16x32_bf16 v[106:109], v[154:157], v[166:169], v[106:109]
	v_mfma_f32_16x16x32_bf16 v[102:105], v[146:149], v[162:165], v[102:105]
	v_mfma_f32_16x16x32_bf16 v[98:101], v[154:157], v[162:165], v[98:101]
	v_mfma_f32_16x16x32_bf16 v[126:129], v[150:153], v[190:193], v[126:129]
	v_mfma_f32_16x16x32_bf16 v[122:125], v[158:161], v[190:193], v[122:125]
	v_mfma_f32_16x16x32_bf16 v[118:121], v[150:153], v[186:189], v[118:121]
	v_mfma_f32_16x16x32_bf16 v[114:117], v[158:161], v[186:189], v[114:117]
	v_mfma_f32_16x16x32_bf16 v[110:113], v[150:153], v[182:185], v[110:113]
	v_mfma_f32_16x16x32_bf16 v[106:109], v[158:161], v[182:185], v[106:109]
	v_mfma_f32_16x16x32_bf16 v[102:105], v[150:153], v[178:181], v[102:105]
	v_mfma_f32_16x16x32_bf16 v[98:101], v[158:161], v[178:181], v[98:101]
	s_setprio 1
	s_setprio 0
	s_add_u32 s72, s68, 0xe0000
	s_addc_u32 s73, s69, 0
	s_add_u32 s70, s70, 0x220000
	s_addc_u32 s71, s71, 0
	v_mfma_f32_16x16x32_bf16 v[94:97], v[130:133], v[174:177], v[94:97]
	v_mfma_f32_16x16x32_bf16 v[90:93], v[138:141], v[174:177], v[90:93]
	v_mfma_f32_16x16x32_bf16 v[86:89], v[130:133], v[170:173], v[86:89]
	v_mfma_f32_16x16x32_bf16 v[82:85], v[138:141], v[170:173], v[82:85]
	v_mfma_f32_16x16x32_bf16 v[78:81], v[130:133], v[166:169], v[78:81]
	v_mfma_f32_16x16x32_bf16 v[74:77], v[138:141], v[166:169], v[74:77]
	v_mfma_f32_16x16x32_bf16 v[70:73], v[130:133], v[162:165], v[70:73]
	v_mfma_f32_16x16x32_bf16 v[66:69], v[138:141], v[162:165], v[66:69]
	v_mfma_f32_16x16x32_bf16 v[94:97], v[134:137], v[190:193], v[94:97]
	v_mfma_f32_16x16x32_bf16 v[90:93], v[142:145], v[190:193], v[90:93]
	v_mfma_f32_16x16x32_bf16 v[86:89], v[134:137], v[186:189], v[86:89]
	v_mfma_f32_16x16x32_bf16 v[82:85], v[142:145], v[186:189], v[82:85]
	v_mfma_f32_16x16x32_bf16 v[78:81], v[134:137], v[182:185], v[78:81]
	v_mfma_f32_16x16x32_bf16 v[74:77], v[142:145], v[182:185], v[74:77]
	v_mfma_f32_16x16x32_bf16 v[70:73], v[134:137], v[178:181], v[70:73]
	v_mfma_f32_16x16x32_bf16 v[66:69], v[142:145], v[178:181], v[66:69]
	s_setprio 1
	s_barrier
	s_and_b64 vcc, exec, s[42:43]
	s_cbranch_vccnz .LBB0_909
	ds_read_b128 v[174:177], v228 offset:49152
	ds_read_b128 v[190:193], v228 offset:50176
	ds_read_b128 v[170:173], v228 offset:51200
	ds_read_b128 v[186:189], v228 offset:52224
	ds_read_b128 v[166:169], v228 offset:53248
	ds_read_b128 v[182:185], v228 offset:54272
	ds_read_b128 v[162:165], v228 offset:55296
	ds_read_b128 v[178:181], v228 offset:56320
.LBB0_909:
	s_mov_b32 m0, s16
	s_add_u32 s68, s68, 0xe4000
	global_load_lds_dwordx4 v194, s[72:73]
	s_mov_b32 m0, s17
	s_addc_u32 s69, s69, 0
	global_load_lds_dwordx4 v196, s[72:73]
	s_mov_b32 m0, s54
	s_and_b64 vcc, exec, s[42:43]
	global_load_lds_dwordx4 v194, s[68:69]
	s_mov_b32 m0, s55
	s_nop 0
	global_load_lds_dwordx4 v196, s[68:69]
	s_mov_b64 s[100:101], s[70:71]
	s_waitcnt vmcnt(6)
	s_waitcnt lgkmcnt(0)
	s_barrier
	s_cbranch_vccnz .LBB0_902
	s_setprio 0
	s_waitcnt lgkmcnt(0)
	v_mfma_f32_16x16x32_bf16 v[62:65], v[146:149], v[174:177], v[62:65]
	v_mfma_f32_16x16x32_bf16 v[58:61], v[154:157], v[174:177], v[58:61]
	v_mfma_f32_16x16x32_bf16 v[54:57], v[146:149], v[170:173], v[54:57]
	v_mfma_f32_16x16x32_bf16 v[50:53], v[154:157], v[170:173], v[50:53]
	v_mfma_f32_16x16x32_bf16 v[46:49], v[146:149], v[166:169], v[46:49]
	v_mfma_f32_16x16x32_bf16 v[42:45], v[154:157], v[166:169], v[42:45]
	v_mfma_f32_16x16x32_bf16 v[38:41], v[146:149], v[162:165], v[38:41]
	v_mfma_f32_16x16x32_bf16 v[34:37], v[154:157], v[162:165], v[34:37]
	v_mfma_f32_16x16x32_bf16 v[62:65], v[150:153], v[190:193], v[62:65]
	v_mfma_f32_16x16x32_bf16 v[58:61], v[158:161], v[190:193], v[58:61]
	v_mfma_f32_16x16x32_bf16 v[54:57], v[150:153], v[186:189], v[54:57]
	v_mfma_f32_16x16x32_bf16 v[50:53], v[158:161], v[186:189], v[50:53]
	v_mfma_f32_16x16x32_bf16 v[46:49], v[150:153], v[182:185], v[46:49]
	v_mfma_f32_16x16x32_bf16 v[42:45], v[158:161], v[182:185], v[42:45]
	v_mfma_f32_16x16x32_bf16 v[38:41], v[150:153], v[178:181], v[38:41]
	v_mfma_f32_16x16x32_bf16 v[34:37], v[158:161], v[178:181], v[34:37]
	s_setprio 1
	s_setprio 0
	v_mfma_f32_16x16x32_bf16 v[30:33], v[130:133], v[174:177], v[30:33]
	v_mfma_f32_16x16x32_bf16 v[26:29], v[138:141], v[174:177], v[26:29]
	v_mfma_f32_16x16x32_bf16 v[22:25], v[130:133], v[170:173], v[22:25]
	v_mfma_f32_16x16x32_bf16 v[18:21], v[138:141], v[170:173], v[18:21]
	v_mfma_f32_16x16x32_bf16 v[14:17], v[130:133], v[166:169], v[14:17]
	v_mfma_f32_16x16x32_bf16 v[10:13], v[138:141], v[166:169], v[10:13]
	v_mfma_f32_16x16x32_bf16 v[6:9], v[130:133], v[162:165], v[6:9]
	v_mfma_f32_16x16x32_bf16 v[2:5], v[138:141], v[162:165], v[2:5]
	v_mfma_f32_16x16x32_bf16 v[30:33], v[134:137], v[190:193], v[30:33]
	v_mfma_f32_16x16x32_bf16 v[26:29], v[142:145], v[190:193], v[26:29]
	v_mfma_f32_16x16x32_bf16 v[22:25], v[134:137], v[186:189], v[22:25]
	v_mfma_f32_16x16x32_bf16 v[18:21], v[142:145], v[186:189], v[18:21]
	v_mfma_f32_16x16x32_bf16 v[14:17], v[134:137], v[182:185], v[14:17]
	v_mfma_f32_16x16x32_bf16 v[10:13], v[142:145], v[182:185], v[10:13]
	v_mfma_f32_16x16x32_bf16 v[6:9], v[134:137], v[178:181], v[6:9]
	v_mfma_f32_16x16x32_bf16 v[2:5], v[142:145], v[178:181], v[2:5]
	s_setprio 1
	s_branch .LBB0_902

.LBB0_1289:
	s_mov_b32 m0, s27
	s_nop 0
	global_load_lds_dwordx4 v194, s[100:101]
	s_mov_b32 m0, s54
	s_nop 0
	global_load_lds_dwordx4 v196, s[100:101]
	v_add_u32_e32 v142, 0x14000, v229
	ds_read_b128 v[146:149], v230
	ds_read_b128 v[150:153], v230 offset:1024
	ds_read_b128 v[154:157], v230 offset:2048
	ds_read_b128 v[158:161], v230 offset:3072
	ds_read_b128 v[130:133], v142
	ds_read_b128 v[134:137], v142 offset:1024
	ds_read_b128 v[138:141], v142 offset:2048
	ds_read_b128 v[142:145], v142 offset:3072
	v_lshl_add_u64 v[234:235], v[222:223], 0, s[48:49]
	s_add_i32 m0, s8, 0xc000
	s_waitcnt lgkmcnt(0)
	ds_read_b128 v[174:177], v231
	ds_read_b128 v[190:193], v231 offset:1024
	ds_read_b128 v[170:173], v231 offset:2048
	ds_read_b128 v[186:189], v231 offset:3072
	ds_read_b128 v[166:169], v231 offset:4096
	ds_read_b128 v[182:185], v231 offset:5120
	ds_read_b128 v[162:165], v231 offset:6144
	ds_read_b128 v[178:181], v231 offset:7168
	global_load_lds_dwordx4 v[234:235], off
	v_lshl_add_u64 v[234:235], v[224:225], 0, s[48:49]
	s_add_i32 m0, s8, 0xe000
	s_nop 0
	global_load_lds_dwordx4 v[234:235], off
	s_waitcnt vmcnt(8)
	s_waitcnt lgkmcnt(0)
	s_barrier
	s_setprio 0
	s_waitcnt lgkmcnt(0)
	v_mfma_f32_16x16x32_bf16 v[126:129], v[146:149], v[174:177], v[126:129]
	v_mfma_f32_16x16x32_bf16 v[122:125], v[154:157], v[174:177], v[122:125]
	v_mfma_f32_16x16x32_bf16 v[118:121], v[146:149], v[170:173], v[118:121]
	v_mfma_f32_16x16x32_bf16 v[110:113], v[154:157], v[170:173], v[110:113]
	v_mfma_f32_16x16x32_bf16 v[102:105], v[146:149], v[166:169], v[102:105]
	v_mfma_f32_16x16x32_bf16 v[94:97], v[154:157], v[166:169], v[94:97]
	v_mfma_f32_16x16x32_bf16 v[86:89], v[146:149], v[162:165], v[86:89]
	v_mfma_f32_16x16x32_bf16 v[78:81], v[154:157], v[162:165], v[78:81]
	v_mfma_f32_16x16x32_bf16 v[126:129], v[150:153], v[190:193], v[126:129]
	v_mfma_f32_16x16x32_bf16 v[122:125], v[158:161], v[190:193], v[122:125]
	v_mfma_f32_16x16x32_bf16 v[118:121], v[150:153], v[186:189], v[118:121]
	v_mfma_f32_16x16x32_bf16 v[110:113], v[158:161], v[186:189], v[110:113]
	v_mfma_f32_16x16x32_bf16 v[102:105], v[150:153], v[182:185], v[102:105]
	v_mfma_f32_16x16x32_bf16 v[94:97], v[158:161], v[182:185], v[94:97]
	v_mfma_f32_16x16x32_bf16 v[86:89], v[150:153], v[178:181], v[86:89]
	v_mfma_f32_16x16x32_bf16 v[78:81], v[158:161], v[178:181], v[78:81]
	s_setprio 1
	s_setprio 0
	s_add_u32 s52, s36, s48
	s_addc_u32 s53, s37, s49
	s_add_u32 s56, s52, 0x440000
	s_addc_u32 s57, s53, 0
	s_cmp_eq_u32 s48, 0x3fc0000
	s_cselect_b64 s[58:59], -1, 0
	s_and_b64 s[52:53], s[58:59], exec
	s_cselect_b32 s53, s31, s63
	s_cselect_b32 s52, s61, s62
	s_cselect_b32 s57, s19, s57
	s_cselect_b32 s56, s29, s56
	v_mfma_f32_16x16x32_bf16 v[114:117], v[130:133], v[174:177], v[114:117]
	v_mfma_f32_16x16x32_bf16 v[106:109], v[138:141], v[174:177], v[106:109]
	v_mfma_f32_16x16x32_bf16 v[98:101], v[130:133], v[170:173], v[98:101]
	v_mfma_f32_16x16x32_bf16 v[90:93], v[138:141], v[170:173], v[90:93]
	v_mfma_f32_16x16x32_bf16 v[82:85], v[130:133], v[166:169], v[82:85]
	v_mfma_f32_16x16x32_bf16 v[74:77], v[138:141], v[166:169], v[74:77]
	v_mfma_f32_16x16x32_bf16 v[70:73], v[130:133], v[162:165], v[70:73]
	v_mfma_f32_16x16x32_bf16 v[66:69], v[138:141], v[162:165], v[66:69]
	v_mfma_f32_16x16x32_bf16 v[114:117], v[134:137], v[190:193], v[114:117]
	v_mfma_f32_16x16x32_bf16 v[106:109], v[142:145], v[190:193], v[106:109]
	v_mfma_f32_16x16x32_bf16 v[98:101], v[134:137], v[186:189], v[98:101]
	v_mfma_f32_16x16x32_bf16 v[90:93], v[142:145], v[186:189], v[90:93]
	v_mfma_f32_16x16x32_bf16 v[82:85], v[134:137], v[182:185], v[82:85]
	v_mfma_f32_16x16x32_bf16 v[74:77], v[142:145], v[182:185], v[74:77]
	v_mfma_f32_16x16x32_bf16 v[70:73], v[134:137], v[178:181], v[70:73]
	v_mfma_f32_16x16x32_bf16 v[66:69], v[142:145], v[178:181], v[66:69]
	s_setprio 1
	s_barrier
	v_cndmask_b32_e64 v233, 0, 1, s[40:41]
	v_cmp_ne_u32_e64 s[42:43], 1, v233
	s_andn2_b64 vcc, exec, s[40:41]
	s_cbranch_vccnz .LBB0_1291
	ds_read_b128 v[174:177], v231 offset:16384
	ds_read_b128 v[190:193], v231 offset:17408
	ds_read_b128 v[170:173], v231 offset:18432
	ds_read_b128 v[186:189], v231 offset:19456
	ds_read_b128 v[166:169], v231 offset:20480
	ds_read_b128 v[182:185], v231 offset:21504
	ds_read_b128 v[162:165], v231 offset:22528
	ds_read_b128 v[178:181], v231 offset:23552
.LBB0_1291:
	s_mov_b32 m0, s9
	s_add_u32 s68, s52, 0x4000
	global_load_lds_dwordx4 v194, s[52:53]
	s_mov_b32 m0, s10
	s_addc_u32 s69, s53, 0
	global_load_lds_dwordx4 v196, s[52:53]
	s_mov_b32 m0, s11
	s_and_b64 vcc, exec, s[42:43]
	global_load_lds_dwordx4 v194, s[68:69]
	s_mov_b32 m0, s12
	s_nop 0
	global_load_lds_dwordx4 v196, s[68:69]
	s_mov_b64 s[98:99], s[56:57]
	s_waitcnt vmcnt(6)
	s_waitcnt lgkmcnt(0)
	s_barrier
	s_cbranch_vccnz .LBB0_1293
	s_setprio 0
	s_waitcnt lgkmcnt(0)
	v_mfma_f32_16x16x32_bf16 v[62:65], v[146:149], v[174:177], v[62:65]
	v_mfma_f32_16x16x32_bf16 v[58:61], v[154:157], v[174:177], v[58:61]
	v_mfma_f32_16x16x32_bf16 v[46:49], v[146:149], v[170:173], v[46:49]
	v_mfma_f32_16x16x32_bf16 v[42:45], v[154:157], v[170:173], v[42:45]
	v_mfma_f32_16x16x32_bf16 v[30:33], v[146:149], v[166:169], v[30:33]
	v_mfma_f32_16x16x32_bf16 v[26:29], v[154:157], v[166:169], v[26:29]
	v_mfma_f32_16x16x32_bf16 v[14:17], v[146:149], v[162:165], v[14:17]
	v_mfma_f32_16x16x32_bf16 v[10:13], v[154:157], v[162:165], v[10:13]
	v_mfma_f32_16x16x32_bf16 v[62:65], v[150:153], v[190:193], v[62:65]
	v_mfma_f32_16x16x32_bf16 v[58:61], v[158:161], v[190:193], v[58:61]
	v_mfma_f32_16x16x32_bf16 v[46:49], v[150:153], v[186:189], v[46:49]
	v_mfma_f32_16x16x32_bf16 v[42:45], v[158:161], v[186:189], v[42:45]
	v_mfma_f32_16x16x32_bf16 v[30:33], v[150:153], v[182:185], v[30:33]
	v_mfma_f32_16x16x32_bf16 v[26:29], v[158:161], v[182:185], v[26:29]
	v_mfma_f32_16x16x32_bf16 v[14:17], v[150:153], v[178:181], v[14:17]
	v_mfma_f32_16x16x32_bf16 v[10:13], v[158:161], v[178:181], v[10:13]
	s_setprio 1
	s_setprio 0
	v_mfma_f32_16x16x32_bf16 v[54:57], v[130:133], v[174:177], v[54:57]
	v_mfma_f32_16x16x32_bf16 v[50:53], v[138:141], v[174:177], v[50:53]
	v_mfma_f32_16x16x32_bf16 v[38:41], v[130:133], v[170:173], v[38:41]
	v_mfma_f32_16x16x32_bf16 v[34:37], v[138:141], v[170:173], v[34:37]
	v_mfma_f32_16x16x32_bf16 v[22:25], v[130:133], v[166:169], v[22:25]
	v_mfma_f32_16x16x32_bf16 v[18:21], v[138:141], v[166:169], v[18:21]
	v_mfma_f32_16x16x32_bf16 v[6:9], v[130:133], v[162:165], v[6:9]
	v_mfma_f32_16x16x32_bf16 v[2:5], v[138:141], v[162:165], v[2:5]
	v_mfma_f32_16x16x32_bf16 v[54:57], v[134:137], v[190:193], v[54:57]
	v_mfma_f32_16x16x32_bf16 v[50:53], v[142:145], v[190:193], v[50:53]
	v_mfma_f32_16x16x32_bf16 v[38:41], v[134:137], v[186:189], v[38:41]
	v_mfma_f32_16x16x32_bf16 v[34:37], v[142:145], v[186:189], v[34:37]
	v_mfma_f32_16x16x32_bf16 v[22:25], v[134:137], v[182:185], v[22:25]
	v_mfma_f32_16x16x32_bf16 v[18:21], v[142:145], v[182:185], v[18:21]
	v_mfma_f32_16x16x32_bf16 v[6:9], v[134:137], v[178:181], v[6:9]
	v_mfma_f32_16x16x32_bf16 v[2:5], v[142:145], v[178:181], v[2:5]
	s_setprio 1
.LBB0_1293:
	s_and_b64 vcc, s[34:35], s[58:59]
	v_cndmask_b32_e64 v131, v221, 0, vcc
	v_cndmask_b32_e32 v130, v220, v198, vcc
	v_lshl_add_u64 v[234:235], s[56:57], 0, v[130:131]
	s_barrier
	s_mov_b32 m0, s8
	s_nop 0
	global_load_lds_dwordx4 v194, s[98:99]
	s_mov_b32 m0, s13
	s_nop 0
	global_load_lds_dwordx4 v196, s[98:99]
	v_add_u32_e32 v130, 0x18000, v229
	v_add_u32_e32 v142, 0x1c000, v229
	ds_read_b128 v[146:149], v130
	ds_read_b128 v[150:153], v130 offset:1024
	ds_read_b128 v[154:157], v130 offset:2048
	ds_read_b128 v[158:161], v130 offset:3072
	ds_read_b128 v[130:133], v142
	ds_read_b128 v[134:137], v142 offset:1024
	ds_read_b128 v[138:141], v142 offset:2048
	ds_read_b128 v[142:145], v142 offset:3072
	s_mov_b32 m0, s14
	v_lshl_add_u64 v[236:237], v[234:235], 0, v[194:195]
	s_waitcnt lgkmcnt(0)
	ds_read_b128 v[174:177], v231 offset:32768
	ds_read_b128 v[190:193], v231 offset:33792
	ds_read_b128 v[170:173], v231 offset:34816
	ds_read_b128 v[186:189], v231 offset:35840
	ds_read_b128 v[166:169], v231 offset:36864
	ds_read_b128 v[182:185], v231 offset:37888
	ds_read_b128 v[162:165], v231 offset:38912
	ds_read_b128 v[178:181], v231 offset:39936
	global_load_lds_dwordx4 v[236:237], off
	v_lshl_add_u64 v[234:235], v[234:235], 0, v[196:197]
	s_mov_b32 m0, s15
	s_nop 0
	global_load_lds_dwordx4 v[234:235], off
	s_waitcnt vmcnt(8)
	s_waitcnt lgkmcnt(0)
	s_barrier
	s_setprio 0
	s_waitcnt lgkmcnt(0)
	v_mfma_f32_16x16x32_bf16 v[126:129], v[146:149], v[174:177], v[126:129]
	v_mfma_f32_16x16x32_bf16 v[122:125], v[154:157], v[174:177], v[122:125]
	v_mfma_f32_16x16x32_bf16 v[118:121], v[146:149], v[170:173], v[118:121]
	v_mfma_f32_16x16x32_bf16 v[110:113], v[154:157], v[170:173], v[110:113]
	v_mfma_f32_16x16x32_bf16 v[102:105], v[146:149], v[166:169], v[102:105]
	v_mfma_f32_16x16x32_bf16 v[94:97], v[154:157], v[166:169], v[94:97]
	v_mfma_f32_16x16x32_bf16 v[86:89], v[146:149], v[162:165], v[86:89]
	v_mfma_f32_16x16x32_bf16 v[78:81], v[154:157], v[162:165], v[78:81]
	v_mfma_f32_16x16x32_bf16 v[126:129], v[150:153], v[190:193], v[126:129]
	v_mfma_f32_16x16x32_bf16 v[122:125], v[158:161], v[190:193], v[122:125]
	v_mfma_f32_16x16x32_bf16 v[118:121], v[150:153], v[186:189], v[118:121]
	v_mfma_f32_16x16x32_bf16 v[110:113], v[158:161], v[186:189], v[110:113]
	v_mfma_f32_16x16x32_bf16 v[102:105], v[150:153], v[182:185], v[102:105]
	v_mfma_f32_16x16x32_bf16 v[94:97], v[158:161], v[182:185], v[94:97]
	v_mfma_f32_16x16x32_bf16 v[86:89], v[150:153], v[178:181], v[86:89]
	v_mfma_f32_16x16x32_bf16 v[78:81], v[158:161], v[178:181], v[78:81]
	s_setprio 1
	s_setprio 0
	s_add_u32 s58, s52, 0x40000
	s_addc_u32 s59, s53, 0
	s_add_u32 s56, s56, 0x220000
	s_addc_u32 s57, s57, 0
	v_mfma_f32_16x16x32_bf16 v[114:117], v[130:133], v[174:177], v[114:117]
	v_mfma_f32_16x16x32_bf16 v[106:109], v[138:141], v[174:177], v[106:109]
	v_mfma_f32_16x16x32_bf16 v[98:101], v[130:133], v[170:173], v[98:101]
	v_mfma_f32_16x16x32_bf16 v[90:93], v[138:141], v[170:173], v[90:93]
	v_mfma_f32_16x16x32_bf16 v[82:85], v[130:133], v[166:169], v[82:85]
	v_mfma_f32_16x16x32_bf16 v[74:77], v[138:141], v[166:169], v[74:77]
	v_mfma_f32_16x16x32_bf16 v[70:73], v[130:133], v[162:165], v[70:73]
	v_mfma_f32_16x16x32_bf16 v[66:69], v[138:141], v[162:165], v[66:69]
	v_mfma_f32_16x16x32_bf16 v[114:117], v[134:137], v[190:193], v[114:117]
	v_mfma_f32_16x16x32_bf16 v[106:109], v[142:145], v[190:193], v[106:109]
	v_mfma_f32_16x16x32_bf16 v[98:101], v[134:137], v[186:189], v[98:101]
	v_mfma_f32_16x16x32_bf16 v[90:93], v[142:145], v[186:189], v[90:93]
	v_mfma_f32_16x16x32_bf16 v[82:85], v[134:137], v[182:185], v[82:85]
	v_mfma_f32_16x16x32_bf16 v[74:77], v[142:145], v[182:185], v[74:77]
	v_mfma_f32_16x16x32_bf16 v[70:73], v[134:137], v[178:181], v[70:73]
	v_mfma_f32_16x16x32_bf16 v[66:69], v[142:145], v[178:181], v[66:69]
	s_setprio 1
	s_barrier
	s_and_b64 vcc, exec, s[42:43]
	s_cbranch_vccnz .LBB0_1295
	ds_read_b128 v[174:177], v231 offset:49152
	ds_read_b128 v[190:193], v231 offset:50176
	ds_read_b128 v[170:173], v231 offset:51200
	ds_read_b128 v[186:189], v231 offset:52224
	ds_read_b128 v[166:169], v231 offset:53248
	ds_read_b128 v[182:185], v231 offset:54272
	ds_read_b128 v[162:165], v231 offset:55296
	ds_read_b128 v[178:181], v231 offset:56320
.LBB0_1295:
	s_mov_b32 m0, s16
	s_add_u32 s52, s52, 0x44000
	global_load_lds_dwordx4 v194, s[58:59]
	s_mov_b32 m0, s17
	s_addc_u32 s53, s53, 0
	global_load_lds_dwordx4 v196, s[58:59]
	s_mov_b32 m0, s55
	s_and_b64 vcc, exec, s[42:43]
	global_load_lds_dwordx4 v194, s[52:53]
	s_mov_b32 m0, s60
	s_nop 0
	global_load_lds_dwordx4 v196, s[52:53]
	s_mov_b64 s[100:101], s[56:57]
	s_waitcnt vmcnt(6)
	s_waitcnt lgkmcnt(0)
	s_barrier
	s_cbranch_vccnz .LBB0_1288
	s_setprio 0
	s_waitcnt lgkmcnt(0)
	v_mfma_f32_16x16x32_bf16 v[62:65], v[146:149], v[174:177], v[62:65]
	v_mfma_f32_16x16x32_bf16 v[58:61], v[154:157], v[174:177], v[58:61]
	v_mfma_f32_16x16x32_bf16 v[46:49], v[146:149], v[170:173], v[46:49]
	v_mfma_f32_16x16x32_bf16 v[42:45], v[154:157], v[170:173], v[42:45]
	v_mfma_f32_16x16x32_bf16 v[30:33], v[146:149], v[166:169], v[30:33]
	v_mfma_f32_16x16x32_bf16 v[26:29], v[154:157], v[166:169], v[26:29]
	v_mfma_f32_16x16x32_bf16 v[14:17], v[146:149], v[162:165], v[14:17]
	v_mfma_f32_16x16x32_bf16 v[10:13], v[154:157], v[162:165], v[10:13]
	v_mfma_f32_16x16x32_bf16 v[62:65], v[150:153], v[190:193], v[62:65]
	v_mfma_f32_16x16x32_bf16 v[58:61], v[158:161], v[190:193], v[58:61]
	v_mfma_f32_16x16x32_bf16 v[46:49], v[150:153], v[186:189], v[46:49]
	v_mfma_f32_16x16x32_bf16 v[42:45], v[158:161], v[186:189], v[42:45]
	v_mfma_f32_16x16x32_bf16 v[30:33], v[150:153], v[182:185], v[30:33]
	v_mfma_f32_16x16x32_bf16 v[26:29], v[158:161], v[182:185], v[26:29]
	v_mfma_f32_16x16x32_bf16 v[14:17], v[150:153], v[178:181], v[14:17]
	v_mfma_f32_16x16x32_bf16 v[10:13], v[158:161], v[178:181], v[10:13]
	s_setprio 1
	s_setprio 0
	v_mfma_f32_16x16x32_bf16 v[54:57], v[130:133], v[174:177], v[54:57]
	v_mfma_f32_16x16x32_bf16 v[50:53], v[138:141], v[174:177], v[50:53]
	v_mfma_f32_16x16x32_bf16 v[38:41], v[130:133], v[170:173], v[38:41]
	v_mfma_f32_16x16x32_bf16 v[34:37], v[138:141], v[170:173], v[34:37]
	v_mfma_f32_16x16x32_bf16 v[22:25], v[130:133], v[166:169], v[22:25]
	v_mfma_f32_16x16x32_bf16 v[18:21], v[138:141], v[166:169], v[18:21]
	v_mfma_f32_16x16x32_bf16 v[6:9], v[130:133], v[162:165], v[6:9]
	v_mfma_f32_16x16x32_bf16 v[2:5], v[138:141], v[162:165], v[2:5]
	v_mfma_f32_16x16x32_bf16 v[54:57], v[134:137], v[190:193], v[54:57]
	v_mfma_f32_16x16x32_bf16 v[50:53], v[142:145], v[190:193], v[50:53]
	v_mfma_f32_16x16x32_bf16 v[38:41], v[134:137], v[186:189], v[38:41]
	v_mfma_f32_16x16x32_bf16 v[34:37], v[142:145], v[186:189], v[34:37]
	v_mfma_f32_16x16x32_bf16 v[22:25], v[134:137], v[182:185], v[22:25]
	v_mfma_f32_16x16x32_bf16 v[18:21], v[142:145], v[182:185], v[18:21]
	v_mfma_f32_16x16x32_bf16 v[6:9], v[134:137], v[178:181], v[6:9]
	v_mfma_f32_16x16x32_bf16 v[2:5], v[142:145], v[178:181], v[2:5]
	s_setprio 1
	s_branch .LBB0_1288

.LBB0_1612:
	s_mov_b32 m0, s54
	s_nop 0
	global_load_lds_dwordx4 v194, s[100:101]
	s_mov_b32 m0, s55
	s_nop 0
	global_load_lds_dwordx4 v196, s[100:101]
	v_add_u32_e32 v1, 0x10000, v232
	ds_read_b128 v[146:149], v1
	ds_read_b128 v[150:153], v1 offset:1024
	ds_read_b128 v[154:157], v1 offset:2048
	ds_read_b128 v[158:161], v1 offset:3072
	v_add_u32_e32 v1, 0x14000, v232
	ds_read_b128 v[130:133], v1
	ds_read_b128 v[134:137], v1 offset:1024
	ds_read_b128 v[138:141], v1 offset:2048
	ds_read_b128 v[142:145], v1 offset:3072
	v_lshl_add_u64 v[236:237], v[226:227], 0, s[48:49]
	s_add_i32 m0, s9, 0xc000
	s_waitcnt lgkmcnt(0)
	ds_read_b128 v[174:177], v233
	ds_read_b128 v[190:193], v233 offset:1024
	ds_read_b128 v[170:173], v233 offset:2048
	ds_read_b128 v[186:189], v233 offset:3072
	ds_read_b128 v[166:169], v233 offset:4096
	ds_read_b128 v[182:185], v233 offset:5120
	ds_read_b128 v[162:165], v233 offset:6144
	ds_read_b128 v[178:181], v233 offset:7168
	global_load_lds_dwordx4 v[236:237], off
	v_lshl_add_u64 v[236:237], v[228:229], 0, s[48:49]
	s_add_i32 m0, s9, 0xe000
	s_nop 0
	global_load_lds_dwordx4 v[236:237], off
	s_waitcnt vmcnt(8)
	s_waitcnt lgkmcnt(0)
	s_barrier
	s_setprio 0
	s_waitcnt lgkmcnt(0)
	v_mfma_f32_16x16x32_bf16 v[126:129], v[146:149], v[174:177], v[126:129]
	v_mfma_f32_16x16x32_bf16 v[122:125], v[154:157], v[174:177], v[122:125]
	v_mfma_f32_16x16x32_bf16 v[118:121], v[146:149], v[170:173], v[118:121]
	v_mfma_f32_16x16x32_bf16 v[110:113], v[154:157], v[170:173], v[110:113]
	v_mfma_f32_16x16x32_bf16 v[102:105], v[146:149], v[166:169], v[102:105]
	v_mfma_f32_16x16x32_bf16 v[94:97], v[154:157], v[166:169], v[94:97]
	v_mfma_f32_16x16x32_bf16 v[86:89], v[146:149], v[162:165], v[86:89]
	v_mfma_f32_16x16x32_bf16 v[78:81], v[154:157], v[162:165], v[78:81]
	v_mfma_f32_16x16x32_bf16 v[126:129], v[150:153], v[190:193], v[126:129]
	v_mfma_f32_16x16x32_bf16 v[122:125], v[158:161], v[190:193], v[122:125]
	v_mfma_f32_16x16x32_bf16 v[118:121], v[150:153], v[186:189], v[118:121]
	v_mfma_f32_16x16x32_bf16 v[110:113], v[158:161], v[186:189], v[110:113]
	v_mfma_f32_16x16x32_bf16 v[102:105], v[150:153], v[182:185], v[102:105]
	v_mfma_f32_16x16x32_bf16 v[94:97], v[158:161], v[182:185], v[94:97]
	v_mfma_f32_16x16x32_bf16 v[86:89], v[150:153], v[178:181], v[86:89]
	v_mfma_f32_16x16x32_bf16 v[78:81], v[158:161], v[178:181], v[78:81]
	s_setprio 1
	s_setprio 0
	s_add_u32 s50, s46, s48
	s_addc_u32 s51, s47, s49
	s_add_u32 s52, s50, 0x440000
	s_addc_u32 s53, s51, 0
	s_cmp_eq_u32 s48, 0x3fc0000
	s_cselect_b64 s[56:57], -1, 0
	s_and_b64 s[50:51], s[56:57], exec
	s_cselect_b32 s51, s31, s61
	s_cselect_b32 s50, s35, s60
	s_cselect_b32 s53, s19, s53
	s_cselect_b32 s52, s20, s52
	v_mfma_f32_16x16x32_bf16 v[114:117], v[130:133], v[174:177], v[114:117]
	v_mfma_f32_16x16x32_bf16 v[106:109], v[138:141], v[174:177], v[106:109]
	v_mfma_f32_16x16x32_bf16 v[98:101], v[130:133], v[170:173], v[98:101]
	v_mfma_f32_16x16x32_bf16 v[90:93], v[138:141], v[170:173], v[90:93]
	v_mfma_f32_16x16x32_bf16 v[82:85], v[130:133], v[166:169], v[82:85]
	v_mfma_f32_16x16x32_bf16 v[74:77], v[138:141], v[166:169], v[74:77]
	v_mfma_f32_16x16x32_bf16 v[70:73], v[130:133], v[162:165], v[70:73]
	v_mfma_f32_16x16x32_bf16 v[66:69], v[138:141], v[162:165], v[66:69]
	v_mfma_f32_16x16x32_bf16 v[114:117], v[134:137], v[190:193], v[114:117]
	v_mfma_f32_16x16x32_bf16 v[106:109], v[142:145], v[190:193], v[106:109]
	v_mfma_f32_16x16x32_bf16 v[98:101], v[134:137], v[186:189], v[98:101]
	v_mfma_f32_16x16x32_bf16 v[90:93], v[142:145], v[186:189], v[90:93]
	v_mfma_f32_16x16x32_bf16 v[82:85], v[134:137], v[182:185], v[82:85]
	v_mfma_f32_16x16x32_bf16 v[74:77], v[142:145], v[182:185], v[74:77]
	v_mfma_f32_16x16x32_bf16 v[70:73], v[134:137], v[178:181], v[70:73]
	v_mfma_f32_16x16x32_bf16 v[66:69], v[142:145], v[178:181], v[66:69]
	s_setprio 1
	s_barrier
	v_cndmask_b32_e64 v1, 0, 1, s[40:41]
	v_cmp_ne_u32_e64 s[42:43], 1, v1
	s_andn2_b64 vcc, exec, s[40:41]
	s_cbranch_vccnz .LBB0_1614
	ds_read_b128 v[174:177], v233 offset:16384
	ds_read_b128 v[190:193], v233 offset:17408
	ds_read_b128 v[170:173], v233 offset:18432
	ds_read_b128 v[186:189], v233 offset:19456
	ds_read_b128 v[166:169], v233 offset:20480
	ds_read_b128 v[182:185], v233 offset:21504
	ds_read_b128 v[162:165], v233 offset:22528
	ds_read_b128 v[178:181], v233 offset:23552
.LBB0_1614:
	s_mov_b32 m0, s10
	s_add_u32 s68, s50, 0x4000
	global_load_lds_dwordx4 v194, s[50:51]
	s_mov_b32 m0, s11
	s_addc_u32 s69, s51, 0
	global_load_lds_dwordx4 v196, s[50:51]
	s_mov_b32 m0, s12
	s_and_b64 vcc, exec, s[42:43]
	global_load_lds_dwordx4 v194, s[68:69]
	s_mov_b32 m0, s13
	s_nop 0
	global_load_lds_dwordx4 v196, s[68:69]
	s_mov_b64 s[98:99], s[52:53]
	s_waitcnt vmcnt(6)
	s_waitcnt lgkmcnt(0)
	s_barrier
	s_cbranch_vccnz .LBB0_1616
	s_setprio 0
	s_waitcnt lgkmcnt(0)
	v_mfma_f32_16x16x32_bf16 v[62:65], v[146:149], v[174:177], v[62:65]
	v_mfma_f32_16x16x32_bf16 v[58:61], v[154:157], v[174:177], v[58:61]
	v_mfma_f32_16x16x32_bf16 v[46:49], v[146:149], v[170:173], v[46:49]
	v_mfma_f32_16x16x32_bf16 v[42:45], v[154:157], v[170:173], v[42:45]
	v_mfma_f32_16x16x32_bf16 v[30:33], v[146:149], v[166:169], v[30:33]
	v_mfma_f32_16x16x32_bf16 v[26:29], v[154:157], v[166:169], v[26:29]
	v_mfma_f32_16x16x32_bf16 v[14:17], v[146:149], v[162:165], v[14:17]
	v_mfma_f32_16x16x32_bf16 v[10:13], v[154:157], v[162:165], v[10:13]
	v_mfma_f32_16x16x32_bf16 v[62:65], v[150:153], v[190:193], v[62:65]
	v_mfma_f32_16x16x32_bf16 v[58:61], v[158:161], v[190:193], v[58:61]
	v_mfma_f32_16x16x32_bf16 v[46:49], v[150:153], v[186:189], v[46:49]
	v_mfma_f32_16x16x32_bf16 v[42:45], v[158:161], v[186:189], v[42:45]
	v_mfma_f32_16x16x32_bf16 v[30:33], v[150:153], v[182:185], v[30:33]
	v_mfma_f32_16x16x32_bf16 v[26:29], v[158:161], v[182:185], v[26:29]
	v_mfma_f32_16x16x32_bf16 v[14:17], v[150:153], v[178:181], v[14:17]
	v_mfma_f32_16x16x32_bf16 v[10:13], v[158:161], v[178:181], v[10:13]
	s_setprio 1
	s_setprio 0
	v_mfma_f32_16x16x32_bf16 v[54:57], v[130:133], v[174:177], v[54:57]
	v_mfma_f32_16x16x32_bf16 v[50:53], v[138:141], v[174:177], v[50:53]
	v_mfma_f32_16x16x32_bf16 v[38:41], v[130:133], v[170:173], v[38:41]
	v_mfma_f32_16x16x32_bf16 v[34:37], v[138:141], v[170:173], v[34:37]
	v_mfma_f32_16x16x32_bf16 v[22:25], v[130:133], v[166:169], v[22:25]
	v_mfma_f32_16x16x32_bf16 v[18:21], v[138:141], v[166:169], v[18:21]
	v_mfma_f32_16x16x32_bf16 v[6:9], v[130:133], v[162:165], v[6:9]
	v_mfma_f32_16x16x32_bf16 v[2:5], v[138:141], v[162:165], v[2:5]
	v_mfma_f32_16x16x32_bf16 v[54:57], v[134:137], v[190:193], v[54:57]
	v_mfma_f32_16x16x32_bf16 v[50:53], v[142:145], v[190:193], v[50:53]
	v_mfma_f32_16x16x32_bf16 v[38:41], v[134:137], v[186:189], v[38:41]
	v_mfma_f32_16x16x32_bf16 v[34:37], v[142:145], v[186:189], v[34:37]
	v_mfma_f32_16x16x32_bf16 v[22:25], v[134:137], v[182:185], v[22:25]
	v_mfma_f32_16x16x32_bf16 v[18:21], v[142:145], v[182:185], v[18:21]
	v_mfma_f32_16x16x32_bf16 v[6:9], v[134:137], v[178:181], v[6:9]
	v_mfma_f32_16x16x32_bf16 v[2:5], v[142:145], v[178:181], v[2:5]
	s_setprio 1
.LBB0_1616:
	s_and_b64 vcc, s[38:39], s[56:57]
	v_cndmask_b32_e64 v131, v225, 0, vcc
	v_cndmask_b32_e32 v130, v224, v198, vcc
	v_lshl_add_u64 v[236:237], s[52:53], 0, v[130:131]
	s_barrier
	s_mov_b32 m0, s9
	s_nop 0
	global_load_lds_dwordx4 v194, s[98:99]
	s_mov_b32 m0, s14
	s_nop 0
	global_load_lds_dwordx4 v196, s[98:99]
	v_add_u32_e32 v1, 0x18000, v232
	ds_read_b128 v[146:149], v1
	ds_read_b128 v[150:153], v1 offset:1024
	ds_read_b128 v[154:157], v1 offset:2048
	ds_read_b128 v[158:161], v1 offset:3072
	v_add_u32_e32 v1, 0x1c000, v232
	ds_read_b128 v[130:133], v1
	ds_read_b128 v[134:137], v1 offset:1024
	ds_read_b128 v[138:141], v1 offset:2048
	ds_read_b128 v[142:145], v1 offset:3072
	s_mov_b32 m0, s15
	v_lshl_add_u64 v[238:239], v[236:237], 0, v[194:195]
	s_waitcnt lgkmcnt(0)
	ds_read_b128 v[174:177], v233 offset:32768
	ds_read_b128 v[190:193], v233 offset:33792
	ds_read_b128 v[170:173], v233 offset:34816
	ds_read_b128 v[186:189], v233 offset:35840
	ds_read_b128 v[166:169], v233 offset:36864
	ds_read_b128 v[182:185], v233 offset:37888
	ds_read_b128 v[162:165], v233 offset:38912
	ds_read_b128 v[178:181], v233 offset:39936
	global_load_lds_dwordx4 v[238:239], off
	v_lshl_add_u64 v[236:237], v[236:237], 0, v[196:197]
	s_mov_b32 m0, s16
	s_nop 0
	global_load_lds_dwordx4 v[236:237], off
	s_waitcnt vmcnt(8)
	s_waitcnt lgkmcnt(0)
	s_barrier
	s_setprio 0
	s_waitcnt lgkmcnt(0)
	v_mfma_f32_16x16x32_bf16 v[126:129], v[146:149], v[174:177], v[126:129]
	v_mfma_f32_16x16x32_bf16 v[122:125], v[154:157], v[174:177], v[122:125]
	v_mfma_f32_16x16x32_bf16 v[118:121], v[146:149], v[170:173], v[118:121]
	v_mfma_f32_16x16x32_bf16 v[110:113], v[154:157], v[170:173], v[110:113]
	v_mfma_f32_16x16x32_bf16 v[102:105], v[146:149], v[166:169], v[102:105]
	v_mfma_f32_16x16x32_bf16 v[94:97], v[154:157], v[166:169], v[94:97]
	v_mfma_f32_16x16x32_bf16 v[86:89], v[146:149], v[162:165], v[86:89]
	v_mfma_f32_16x16x32_bf16 v[78:81], v[154:157], v[162:165], v[78:81]
	v_mfma_f32_16x16x32_bf16 v[126:129], v[150:153], v[190:193], v[126:129]
	v_mfma_f32_16x16x32_bf16 v[122:125], v[158:161], v[190:193], v[122:125]
	v_mfma_f32_16x16x32_bf16 v[118:121], v[150:153], v[186:189], v[118:121]
	v_mfma_f32_16x16x32_bf16 v[110:113], v[158:161], v[186:189], v[110:113]
	v_mfma_f32_16x16x32_bf16 v[102:105], v[150:153], v[182:185], v[102:105]
	v_mfma_f32_16x16x32_bf16 v[94:97], v[158:161], v[182:185], v[94:97]
	v_mfma_f32_16x16x32_bf16 v[86:89], v[150:153], v[178:181], v[86:89]
	v_mfma_f32_16x16x32_bf16 v[78:81], v[158:161], v[178:181], v[78:81]
	s_setprio 1
	s_setprio 0
	s_add_u32 s56, s50, 0x40000
	s_addc_u32 s57, s51, 0
	s_add_u32 s52, s52, 0x220000
	s_addc_u32 s53, s53, 0
	v_mfma_f32_16x16x32_bf16 v[114:117], v[130:133], v[174:177], v[114:117]
	v_mfma_f32_16x16x32_bf16 v[106:109], v[138:141], v[174:177], v[106:109]
	v_mfma_f32_16x16x32_bf16 v[98:101], v[130:133], v[170:173], v[98:101]
	v_mfma_f32_16x16x32_bf16 v[90:93], v[138:141], v[170:173], v[90:93]
	v_mfma_f32_16x16x32_bf16 v[82:85], v[130:133], v[166:169], v[82:85]
	v_mfma_f32_16x16x32_bf16 v[74:77], v[138:141], v[166:169], v[74:77]
	v_mfma_f32_16x16x32_bf16 v[70:73], v[130:133], v[162:165], v[70:73]
	v_mfma_f32_16x16x32_bf16 v[66:69], v[138:141], v[162:165], v[66:69]
	v_mfma_f32_16x16x32_bf16 v[114:117], v[134:137], v[190:193], v[114:117]
	v_mfma_f32_16x16x32_bf16 v[106:109], v[142:145], v[190:193], v[106:109]
	v_mfma_f32_16x16x32_bf16 v[98:101], v[134:137], v[186:189], v[98:101]
	v_mfma_f32_16x16x32_bf16 v[90:93], v[142:145], v[186:189], v[90:93]
	v_mfma_f32_16x16x32_bf16 v[82:85], v[134:137], v[182:185], v[82:85]
	v_mfma_f32_16x16x32_bf16 v[74:77], v[142:145], v[182:185], v[74:77]
	v_mfma_f32_16x16x32_bf16 v[70:73], v[134:137], v[178:181], v[70:73]
	v_mfma_f32_16x16x32_bf16 v[66:69], v[142:145], v[178:181], v[66:69]
	s_setprio 1
	s_barrier
	s_and_b64 vcc, exec, s[42:43]
	s_cbranch_vccnz .LBB0_1618
	ds_read_b128 v[174:177], v233 offset:49152
	ds_read_b128 v[190:193], v233 offset:50176
	ds_read_b128 v[170:173], v233 offset:51200
	ds_read_b128 v[186:189], v233 offset:52224
	ds_read_b128 v[166:169], v233 offset:53248
	ds_read_b128 v[182:185], v233 offset:54272
	ds_read_b128 v[162:165], v233 offset:55296
	ds_read_b128 v[178:181], v233 offset:56320
.LBB0_1618:
	s_mov_b32 m0, s17
	s_add_u32 s50, s50, 0x44000
	global_load_lds_dwordx4 v194, s[56:57]
	s_mov_b32 m0, s29
	s_addc_u32 s51, s51, 0
	global_load_lds_dwordx4 v196, s[56:57]
	s_mov_b32 m0, s58
	s_and_b64 vcc, exec, s[42:43]
	global_load_lds_dwordx4 v194, s[50:51]
	s_mov_b32 m0, s59
	s_nop 0
	global_load_lds_dwordx4 v196, s[50:51]
	s_mov_b64 s[100:101], s[52:53]
	s_waitcnt vmcnt(6)
	s_waitcnt lgkmcnt(0)
	s_barrier
	s_cbranch_vccnz .LBB0_1611
	s_setprio 0
	s_waitcnt lgkmcnt(0)
	v_mfma_f32_16x16x32_bf16 v[62:65], v[146:149], v[174:177], v[62:65]
	v_mfma_f32_16x16x32_bf16 v[58:61], v[154:157], v[174:177], v[58:61]
	v_mfma_f32_16x16x32_bf16 v[46:49], v[146:149], v[170:173], v[46:49]
	v_mfma_f32_16x16x32_bf16 v[42:45], v[154:157], v[170:173], v[42:45]
	v_mfma_f32_16x16x32_bf16 v[30:33], v[146:149], v[166:169], v[30:33]
	v_mfma_f32_16x16x32_bf16 v[26:29], v[154:157], v[166:169], v[26:29]
	v_mfma_f32_16x16x32_bf16 v[14:17], v[146:149], v[162:165], v[14:17]
	v_mfma_f32_16x16x32_bf16 v[10:13], v[154:157], v[162:165], v[10:13]
	v_mfma_f32_16x16x32_bf16 v[62:65], v[150:153], v[190:193], v[62:65]
	v_mfma_f32_16x16x32_bf16 v[58:61], v[158:161], v[190:193], v[58:61]
	v_mfma_f32_16x16x32_bf16 v[46:49], v[150:153], v[186:189], v[46:49]
	v_mfma_f32_16x16x32_bf16 v[42:45], v[158:161], v[186:189], v[42:45]
	v_mfma_f32_16x16x32_bf16 v[30:33], v[150:153], v[182:185], v[30:33]
	v_mfma_f32_16x16x32_bf16 v[26:29], v[158:161], v[182:185], v[26:29]
	v_mfma_f32_16x16x32_bf16 v[14:17], v[150:153], v[178:181], v[14:17]
	v_mfma_f32_16x16x32_bf16 v[10:13], v[158:161], v[178:181], v[10:13]
	s_setprio 1
	s_setprio 0
	v_mfma_f32_16x16x32_bf16 v[54:57], v[130:133], v[174:177], v[54:57]
	v_mfma_f32_16x16x32_bf16 v[50:53], v[138:141], v[174:177], v[50:53]
	v_mfma_f32_16x16x32_bf16 v[38:41], v[130:133], v[170:173], v[38:41]
	v_mfma_f32_16x16x32_bf16 v[34:37], v[138:141], v[170:173], v[34:37]
	v_mfma_f32_16x16x32_bf16 v[22:25], v[130:133], v[166:169], v[22:25]
	v_mfma_f32_16x16x32_bf16 v[18:21], v[138:141], v[166:169], v[18:21]
	v_mfma_f32_16x16x32_bf16 v[6:9], v[130:133], v[162:165], v[6:9]
	v_mfma_f32_16x16x32_bf16 v[2:5], v[138:141], v[162:165], v[2:5]
	v_mfma_f32_16x16x32_bf16 v[54:57], v[134:137], v[190:193], v[54:57]
	v_mfma_f32_16x16x32_bf16 v[50:53], v[142:145], v[190:193], v[50:53]
	v_mfma_f32_16x16x32_bf16 v[38:41], v[134:137], v[186:189], v[38:41]
	v_mfma_f32_16x16x32_bf16 v[34:37], v[142:145], v[186:189], v[34:37]
	v_mfma_f32_16x16x32_bf16 v[22:25], v[134:137], v[182:185], v[22:25]
	v_mfma_f32_16x16x32_bf16 v[18:21], v[142:145], v[182:185], v[18:21]
	v_mfma_f32_16x16x32_bf16 v[6:9], v[134:137], v[178:181], v[6:9]
	v_mfma_f32_16x16x32_bf16 v[2:5], v[142:145], v[178:181], v[2:5]
	s_setprio 1
	s_branch .LBB0_1611
